# stack: v114 + coalesced attention epilogue + retA two-deep prefetch + hand-written gate passes (prefetch, DPP reductions)
# baseline (speedup 1.0000x reference)
.LBB0_392:
	s_andn2_b64 vcc, exec, s[12:13]
	s_waitcnt vmcnt(0)
	s_barrier
	s_cbranch_vccnz .LBB0_396
	s_cmpk_gt_i32 s26, 0x3fff
	v_mbcnt_lo_u32_b32 v0, -1, 0
	v_mbcnt_hi_u32_b32 v0, -1, v0
	s_cbranch_scc1 .LBB0_396
	v_mbcnt_lo_u32_b32 v220, -1, 0
	v_mbcnt_hi_u32_b32 v220, -1, v220
	v_mov_b32_e32 v223, 0x3727c5ac
	v_lshlrev_b32_e32 v220, 4, v220
	v_add_u32_e32 v221, 0x1000, v220
	v_add_u32_e32 v222, 0x2000, v220
	s_mov_b32 s20, s26
	s_lshl_b32 s0, s20, 1
	s_and_b32 s0, s0, 0xffffe000
	s_and_b32 s1, s20, 0xfff
	s_or_b32 s0, s0, s1
	s_mulk_i32 s0, 0x3000
	s_add_u32 s14, s62, s0
	s_addc_u32 s15, s63, 0
	global_load_dwordx4 v[0:3], v221, s[14:15] nt
	global_load_dwordx4 v[16:19], v222, s[14:15] nt
	global_load_dwordx4 v[4:7], v221, s[14:15] offset:1024 nt
	global_load_dwordx4 v[20:23], v222, s[14:15] offset:1024 nt
	global_load_dwordx4 v[8:11], v221, s[14:15] offset:2048 nt
	global_load_dwordx4 v[24:27], v222, s[14:15] offset:2048 nt
	global_load_dwordx4 v[12:15], v221, s[14:15] offset:3072 nt
	global_load_dwordx4 v[28:31], v222, s[14:15] offset:3072 nt
	s_mov_b64 s[16:17], s[14:15]
	s_add_i32 s21, s20, s82
	s_cmpk_lt_i32 s21, 0x4000
	s_cbranch_scc0 .Lgate0_nopfAf
	s_lshl_b32 s0, s21, 1
	s_and_b32 s0, s0, 0xffffe000
	s_and_b32 s1, s21, 0xfff
	s_or_b32 s0, s0, s1
	s_mulk_i32 s0, 0x3000
	s_add_u32 s14, s62, s0
	s_addc_u32 s15, s63, 0
	global_load_dwordx4 v[48:51], v221, s[14:15] nt
	global_load_dwordx4 v[64:67], v222, s[14:15] nt
	global_load_dwordx4 v[52:55], v221, s[14:15] offset:1024 nt
	global_load_dwordx4 v[68:71], v222, s[14:15] offset:1024 nt
	global_load_dwordx4 v[56:59], v221, s[14:15] offset:2048 nt
	global_load_dwordx4 v[72:75], v222, s[14:15] offset:2048 nt
	global_load_dwordx4 v[60:63], v221, s[14:15] offset:3072 nt
	global_load_dwordx4 v[76:79], v222, s[14:15] offset:3072 nt
	s_waitcnt vmcnt(8)
	s_branch .Lgate0_goA

.Lgate0_topA:
	s_add_i32 s21, s20, s82
	s_cmpk_lt_i32 s21, 0x4000
	s_cbranch_scc0 .Lgate0_nopfA
	s_lshl_b32 s0, s21, 1
	s_and_b32 s0, s0, 0xffffe000
	s_and_b32 s1, s21, 0xfff
	s_or_b32 s0, s0, s1
	s_mulk_i32 s0, 0x3000
	s_add_u32 s14, s62, s0
	s_addc_u32 s15, s63, 0
	global_load_dwordx4 v[48:51], v221, s[14:15] nt
	global_load_dwordx4 v[64:67], v222, s[14:15] nt
	global_load_dwordx4 v[52:55], v221, s[14:15] offset:1024 nt
	global_load_dwordx4 v[68:71], v222, s[14:15] offset:1024 nt
	global_load_dwordx4 v[56:59], v221, s[14:15] offset:2048 nt
	global_load_dwordx4 v[72:75], v222, s[14:15] offset:2048 nt
	global_load_dwordx4 v[60:63], v221, s[14:15] offset:3072 nt
	global_load_dwordx4 v[76:79], v222, s[14:15] offset:3072 nt
	s_waitcnt vmcnt(12)
	s_branch .Lgate0_goA

.Lgate0_goA:
	v_lshlrev_b32_e32 v96, 16, v0
	v_and_b32_e32 v97, 0xffff0000, v0
	v_lshlrev_b32_e32 v98, 16, v1
	v_and_b32_e32 v99, 0xffff0000, v1
	v_lshlrev_b32_e32 v100, 16, v2
	v_and_b32_e32 v101, 0xffff0000, v2
	v_lshlrev_b32_e32 v102, 16, v3
	v_and_b32_e32 v103, 0xffff0000, v3
	v_mul_f32_e32 v192, v96, v96
	v_fmac_f32_e32 v192, v97, v97
	v_fmac_f32_e32 v192, v98, v98
	v_fmac_f32_e32 v192, v99, v99
	v_fmac_f32_e32 v192, v100, v100
	v_fmac_f32_e32 v192, v101, v101
	v_fmac_f32_e32 v192, v102, v102
	v_fmac_f32_e32 v192, v103, v103
	v_lshlrev_b32_e32 v104, 16, v4
	v_and_b32_e32 v105, 0xffff0000, v4
	v_lshlrev_b32_e32 v106, 16, v5
	v_and_b32_e32 v107, 0xffff0000, v5
	v_lshlrev_b32_e32 v108, 16, v6
	v_and_b32_e32 v109, 0xffff0000, v6
	v_lshlrev_b32_e32 v110, 16, v7
	v_and_b32_e32 v111, 0xffff0000, v7
	v_mul_f32_e32 v193, v104, v104
	v_fmac_f32_e32 v193, v105, v105
	v_fmac_f32_e32 v193, v106, v106
	v_fmac_f32_e32 v193, v107, v107
	v_fmac_f32_e32 v193, v108, v108
	v_fmac_f32_e32 v193, v109, v109
	v_fmac_f32_e32 v193, v110, v110
	v_fmac_f32_e32 v193, v111, v111
	v_lshlrev_b32_e32 v112, 16, v8
	v_and_b32_e32 v113, 0xffff0000, v8
	v_lshlrev_b32_e32 v114, 16, v9
	v_and_b32_e32 v115, 0xffff0000, v9
	v_lshlrev_b32_e32 v116, 16, v10
	v_and_b32_e32 v117, 0xffff0000, v10
	v_lshlrev_b32_e32 v118, 16, v11
	v_and_b32_e32 v119, 0xffff0000, v11
	v_mul_f32_e32 v194, v112, v112
	v_fmac_f32_e32 v194, v113, v113
	v_fmac_f32_e32 v194, v114, v114
	v_fmac_f32_e32 v194, v115, v115
	v_fmac_f32_e32 v194, v116, v116
	v_fmac_f32_e32 v194, v117, v117
	v_fmac_f32_e32 v194, v118, v118
	v_fmac_f32_e32 v194, v119, v119
	v_lshlrev_b32_e32 v120, 16, v12
	v_and_b32_e32 v121, 0xffff0000, v12
	v_lshlrev_b32_e32 v122, 16, v13
	v_and_b32_e32 v123, 0xffff0000, v13
	v_lshlrev_b32_e32 v124, 16, v14
	v_and_b32_e32 v125, 0xffff0000, v14
	v_lshlrev_b32_e32 v126, 16, v15
	v_and_b32_e32 v127, 0xffff0000, v15
	v_mul_f32_e32 v195, v120, v120
	v_fmac_f32_e32 v195, v121, v121
	v_fmac_f32_e32 v195, v122, v122
	v_fmac_f32_e32 v195, v123, v123
	v_fmac_f32_e32 v195, v124, v124
	v_fmac_f32_e32 v195, v125, v125
	v_fmac_f32_e32 v195, v126, v126
	v_fmac_f32_e32 v195, v127, v127
	s_nop 1
	v_add_f32_dpp v196, v192, v192 quad_perm:[1,0,3,2] row_mask:0xf bank_mask:0xf
	v_add_f32_dpp v197, v193, v193 quad_perm:[1,0,3,2] row_mask:0xf bank_mask:0xf
	v_add_f32_dpp v198, v194, v194 quad_perm:[1,0,3,2] row_mask:0xf bank_mask:0xf
	v_add_f32_dpp v199, v195, v195 quad_perm:[1,0,3,2] row_mask:0xf bank_mask:0xf
	v_add_f32_dpp v192, v196, v196 quad_perm:[2,3,0,1] row_mask:0xf bank_mask:0xf
	v_add_f32_dpp v193, v197, v197 quad_perm:[2,3,0,1] row_mask:0xf bank_mask:0xf
	v_add_f32_dpp v194, v198, v198 quad_perm:[2,3,0,1] row_mask:0xf bank_mask:0xf
	v_add_f32_dpp v195, v199, v199 quad_perm:[2,3,0,1] row_mask:0xf bank_mask:0xf
	v_add_f32_dpp v196, v192, v192 row_half_mirror row_mask:0xf bank_mask:0xf
	v_add_f32_dpp v197, v193, v193 row_half_mirror row_mask:0xf bank_mask:0xf
	v_add_f32_dpp v198, v194, v194 row_half_mirror row_mask:0xf bank_mask:0xf
	v_add_f32_dpp v199, v195, v195 row_half_mirror row_mask:0xf bank_mask:0xf
	v_add_f32_dpp v192, v196, v196 row_mirror row_mask:0xf bank_mask:0xf
	v_add_f32_dpp v193, v197, v197 row_mirror row_mask:0xf bank_mask:0xf
	v_add_f32_dpp v194, v198, v198 row_mirror row_mask:0xf bank_mask:0xf
	v_add_f32_dpp v195, v199, v199 row_mirror row_mask:0xf bank_mask:0xf
	s_nop 0
	v_readlane_b32 s0, v192, 0
	v_readlane_b32 s1, v192, 16
	v_readlane_b32 s6, v192, 32
	v_readlane_b32 s7, v192, 48
	s_nop 1
	v_mov_b32_e32 v196, s0
	v_add_f32_e32 v196, s1, v196
	v_add_f32_e32 v196, s6, v196
	v_add_f32_e32 v196, s7, v196
	v_fmamk_f32 v196, v196, 0x3b000000, v223
	v_readlane_b32 s0, v193, 0
	v_readlane_b32 s1, v193, 16
	v_readlane_b32 s6, v193, 32
	v_readlane_b32 s7, v193, 48
	s_nop 1
	v_mov_b32_e32 v197, s0
	v_add_f32_e32 v197, s1, v197
	v_add_f32_e32 v197, s6, v197
	v_add_f32_e32 v197, s7, v197
	v_fmamk_f32 v197, v197, 0x3b000000, v223
	v_readlane_b32 s0, v194, 0
	v_readlane_b32 s1, v194, 16
	v_readlane_b32 s6, v194, 32
	v_readlane_b32 s7, v194, 48
	s_nop 1
	v_mov_b32_e32 v198, s0
	v_add_f32_e32 v198, s1, v198
	v_add_f32_e32 v198, s6, v198
	v_add_f32_e32 v198, s7, v198
	v_fmamk_f32 v198, v198, 0x3b000000, v223
	v_readlane_b32 s0, v195, 0
	v_readlane_b32 s1, v195, 16
	v_readlane_b32 s6, v195, 32
	v_readlane_b32 s7, v195, 48
	s_nop 1
	v_mov_b32_e32 v199, s0
	v_add_f32_e32 v199, s1, v199
	v_add_f32_e32 v199, s6, v199
	v_add_f32_e32 v199, s7, v199
	v_fmamk_f32 v199, v199, 0x3b000000, v223
	v_rsq_f32_e32 v200, v196
	v_rsq_f32_e32 v201, v197
	v_rsq_f32_e32 v202, v198
	v_rsq_f32_e32 v203, v199
	v_lshlrev_b32_e32 v128, 16, v16
	v_and_b32_e32 v129, 0xffff0000, v16
	v_lshlrev_b32_e32 v130, 16, v17
	v_and_b32_e32 v131, 0xffff0000, v17
	v_lshlrev_b32_e32 v132, 16, v18
	v_and_b32_e32 v133, 0xffff0000, v18
	v_lshlrev_b32_e32 v134, 16, v19
	v_and_b32_e32 v135, 0xffff0000, v19
	v_lshlrev_b32_e32 v136, 16, v20
	v_and_b32_e32 v137, 0xffff0000, v20
	v_lshlrev_b32_e32 v138, 16, v21
	v_and_b32_e32 v139, 0xffff0000, v21
	v_lshlrev_b32_e32 v140, 16, v22
	v_and_b32_e32 v141, 0xffff0000, v22
	v_lshlrev_b32_e32 v142, 16, v23
	v_and_b32_e32 v143, 0xffff0000, v23
	v_lshlrev_b32_e32 v144, 16, v24
	v_and_b32_e32 v145, 0xffff0000, v24
	v_lshlrev_b32_e32 v146, 16, v25
	v_and_b32_e32 v147, 0xffff0000, v25
	v_lshlrev_b32_e32 v148, 16, v26
	v_and_b32_e32 v149, 0xffff0000, v26
	v_lshlrev_b32_e32 v150, 16, v27
	v_and_b32_e32 v151, 0xffff0000, v27
	v_lshlrev_b32_e32 v152, 16, v28
	v_and_b32_e32 v153, 0xffff0000, v28
	v_lshlrev_b32_e32 v154, 16, v29
	v_and_b32_e32 v155, 0xffff0000, v29
	v_lshlrev_b32_e32 v156, 16, v30
	v_and_b32_e32 v157, 0xffff0000, v30
	v_lshlrev_b32_e32 v158, 16, v31
	v_and_b32_e32 v159, 0xffff0000, v31
	v_mul_f32_e32 v160, 0xbfb8aa3b, v128
	v_mul_f32_e32 v161, 0xbfb8aa3b, v129
	v_mul_f32_e32 v162, 0xbfb8aa3b, v130
	v_mul_f32_e32 v163, 0xbfb8aa3b, v131
	v_mul_f32_e32 v164, 0xbfb8aa3b, v132
	v_mul_f32_e32 v165, 0xbfb8aa3b, v133
	v_mul_f32_e32 v166, 0xbfb8aa3b, v134
	v_mul_f32_e32 v167, 0xbfb8aa3b, v135
	v_mul_f32_e32 v168, 0xbfb8aa3b, v136
	v_mul_f32_e32 v169, 0xbfb8aa3b, v137
	v_mul_f32_e32 v170, 0xbfb8aa3b, v138
	v_mul_f32_e32 v171, 0xbfb8aa3b, v139
	v_mul_f32_e32 v172, 0xbfb8aa3b, v140
	v_mul_f32_e32 v173, 0xbfb8aa3b, v141
	v_mul_f32_e32 v174, 0xbfb8aa3b, v142
	v_mul_f32_e32 v175, 0xbfb8aa3b, v143
	v_mul_f32_e32 v176, 0xbfb8aa3b, v144
	v_mul_f32_e32 v177, 0xbfb8aa3b, v145
	v_mul_f32_e32 v178, 0xbfb8aa3b, v146
	v_mul_f32_e32 v179, 0xbfb8aa3b, v147
	v_mul_f32_e32 v180, 0xbfb8aa3b, v148
	v_mul_f32_e32 v181, 0xbfb8aa3b, v149
	v_mul_f32_e32 v182, 0xbfb8aa3b, v150
	v_mul_f32_e32 v183, 0xbfb8aa3b, v151
	v_mul_f32_e32 v184, 0xbfb8aa3b, v152
	v_mul_f32_e32 v185, 0xbfb8aa3b, v153
	v_mul_f32_e32 v186, 0xbfb8aa3b, v154
	v_mul_f32_e32 v187, 0xbfb8aa3b, v155
	v_mul_f32_e32 v188, 0xbfb8aa3b, v156
	v_mul_f32_e32 v189, 0xbfb8aa3b, v157
	v_mul_f32_e32 v190, 0xbfb8aa3b, v158
	v_mul_f32_e32 v191, 0xbfb8aa3b, v159
	v_exp_f32_e32 v160, v160
	v_exp_f32_e32 v161, v161
	v_exp_f32_e32 v162, v162
	v_exp_f32_e32 v163, v163
	v_exp_f32_e32 v164, v164
	v_exp_f32_e32 v165, v165
	v_exp_f32_e32 v166, v166
	v_exp_f32_e32 v167, v167
	v_exp_f32_e32 v168, v168
	v_exp_f32_e32 v169, v169
	v_exp_f32_e32 v170, v170
	v_exp_f32_e32 v171, v171
	v_exp_f32_e32 v172, v172
	v_exp_f32_e32 v173, v173
	v_exp_f32_e32 v174, v174
	v_exp_f32_e32 v175, v175
	v_exp_f32_e32 v176, v176
	v_exp_f32_e32 v177, v177
	v_exp_f32_e32 v178, v178
	v_exp_f32_e32 v179, v179
	v_exp_f32_e32 v180, v180
	v_exp_f32_e32 v181, v181
	v_exp_f32_e32 v182, v182
	v_exp_f32_e32 v183, v183
	v_exp_f32_e32 v184, v184
	v_exp_f32_e32 v185, v185
	v_exp_f32_e32 v186, v186
	v_exp_f32_e32 v187, v187
	v_exp_f32_e32 v188, v188
	v_exp_f32_e32 v189, v189
	v_exp_f32_e32 v190, v190
	v_exp_f32_e32 v191, v191
	v_add_f32_e32 v160, 1.0, v160
	v_add_f32_e32 v161, 1.0, v161
	v_add_f32_e32 v162, 1.0, v162
	v_add_f32_e32 v163, 1.0, v163
	v_add_f32_e32 v164, 1.0, v164
	v_add_f32_e32 v165, 1.0, v165
	v_add_f32_e32 v166, 1.0, v166
	v_add_f32_e32 v167, 1.0, v167
	v_add_f32_e32 v168, 1.0, v168
	v_add_f32_e32 v169, 1.0, v169
	v_add_f32_e32 v170, 1.0, v170
	v_add_f32_e32 v171, 1.0, v171
	v_add_f32_e32 v172, 1.0, v172
	v_add_f32_e32 v173, 1.0, v173
	v_add_f32_e32 v174, 1.0, v174
	v_add_f32_e32 v175, 1.0, v175
	v_add_f32_e32 v176, 1.0, v176
	v_add_f32_e32 v177, 1.0, v177
	v_add_f32_e32 v178, 1.0, v178
	v_add_f32_e32 v179, 1.0, v179
	v_add_f32_e32 v180, 1.0, v180
	v_add_f32_e32 v181, 1.0, v181
	v_add_f32_e32 v182, 1.0, v182
	v_add_f32_e32 v183, 1.0, v183
	v_add_f32_e32 v184, 1.0, v184
	v_add_f32_e32 v185, 1.0, v185
	v_add_f32_e32 v186, 1.0, v186
	v_add_f32_e32 v187, 1.0, v187
	v_add_f32_e32 v188, 1.0, v188
	v_add_f32_e32 v189, 1.0, v189
	v_add_f32_e32 v190, 1.0, v190
	v_add_f32_e32 v191, 1.0, v191
	v_rcp_f32_e32 v160, v160
	v_rcp_f32_e32 v161, v161
	v_rcp_f32_e32 v162, v162
	v_rcp_f32_e32 v163, v163
	v_rcp_f32_e32 v164, v164
	v_rcp_f32_e32 v165, v165
	v_rcp_f32_e32 v166, v166
	v_rcp_f32_e32 v167, v167
	v_rcp_f32_e32 v168, v168
	v_rcp_f32_e32 v169, v169
	v_rcp_f32_e32 v170, v170
	v_rcp_f32_e32 v171, v171
	v_rcp_f32_e32 v172, v172
	v_rcp_f32_e32 v173, v173
	v_rcp_f32_e32 v174, v174
	v_rcp_f32_e32 v175, v175
	v_rcp_f32_e32 v176, v176
	v_rcp_f32_e32 v177, v177
	v_rcp_f32_e32 v178, v178
	v_rcp_f32_e32 v179, v179
	v_rcp_f32_e32 v180, v180
	v_rcp_f32_e32 v181, v181
	v_rcp_f32_e32 v182, v182
	v_rcp_f32_e32 v183, v183
	v_rcp_f32_e32 v184, v184
	v_rcp_f32_e32 v185, v185
	v_rcp_f32_e32 v186, v186
	v_rcp_f32_e32 v187, v187
	v_rcp_f32_e32 v188, v188
	v_rcp_f32_e32 v189, v189
	v_rcp_f32_e32 v190, v190
	v_rcp_f32_e32 v191, v191
	v_mul_f32_e32 v128, v160, v128
	v_mul_f32_e32 v129, v161, v129
	v_mul_f32_e32 v130, v162, v130
	v_mul_f32_e32 v131, v163, v131
	v_mul_f32_e32 v132, v164, v132
	v_mul_f32_e32 v133, v165, v133
	v_mul_f32_e32 v134, v166, v134
	v_mul_f32_e32 v135, v167, v135
	v_mul_f32_e32 v136, v168, v136
	v_mul_f32_e32 v137, v169, v137
	v_mul_f32_e32 v138, v170, v138
	v_mul_f32_e32 v139, v171, v139
	v_mul_f32_e32 v140, v172, v140
	v_mul_f32_e32 v141, v173, v141
	v_mul_f32_e32 v142, v174, v142
	v_mul_f32_e32 v143, v175, v143
	v_mul_f32_e32 v144, v176, v144
	v_mul_f32_e32 v145, v177, v145
	v_mul_f32_e32 v146, v178, v146
	v_mul_f32_e32 v147, v179, v147
	v_mul_f32_e32 v148, v180, v148
	v_mul_f32_e32 v149, v181, v149
	v_mul_f32_e32 v150, v182, v150
	v_mul_f32_e32 v151, v183, v151
	v_mul_f32_e32 v152, v184, v152
	v_mul_f32_e32 v153, v185, v153
	v_mul_f32_e32 v154, v186, v154
	v_mul_f32_e32 v155, v187, v155
	v_mul_f32_e32 v156, v188, v156
	v_mul_f32_e32 v157, v189, v157
	v_mul_f32_e32 v158, v190, v158
	v_mul_f32_e32 v159, v191, v159
	v_mul_f32_e32 v128, v128, v96
	v_mul_f32_e32 v129, v129, v97
	v_mul_f32_e32 v130, v130, v98
	v_mul_f32_e32 v131, v131, v99
	v_mul_f32_e32 v132, v132, v100
	v_mul_f32_e32 v133, v133, v101
	v_mul_f32_e32 v134, v134, v102
	v_mul_f32_e32 v135, v135, v103
	v_mul_f32_e32 v136, v136, v104
	v_mul_f32_e32 v137, v137, v105
	v_mul_f32_e32 v138, v138, v106
	v_mul_f32_e32 v139, v139, v107
	v_mul_f32_e32 v140, v140, v108
	v_mul_f32_e32 v141, v141, v109
	v_mul_f32_e32 v142, v142, v110
	v_mul_f32_e32 v143, v143, v111
	v_mul_f32_e32 v144, v144, v112
	v_mul_f32_e32 v145, v145, v113
	v_mul_f32_e32 v146, v146, v114
	v_mul_f32_e32 v147, v147, v115
	v_mul_f32_e32 v148, v148, v116
	v_mul_f32_e32 v149, v149, v117
	v_mul_f32_e32 v150, v150, v118
	v_mul_f32_e32 v151, v151, v119
	v_mul_f32_e32 v152, v152, v120
	v_mul_f32_e32 v153, v153, v121
	v_mul_f32_e32 v154, v154, v122
	v_mul_f32_e32 v155, v155, v123
	v_mul_f32_e32 v156, v156, v124
	v_mul_f32_e32 v157, v157, v125
	v_mul_f32_e32 v158, v158, v126
	v_mul_f32_e32 v159, v159, v127
	v_mul_f32_e32 v128, v128, v200
	v_mul_f32_e32 v129, v129, v200
	v_mul_f32_e32 v130, v130, v200
	v_mul_f32_e32 v131, v131, v200
	v_mul_f32_e32 v132, v132, v200
	v_mul_f32_e32 v133, v133, v200
	v_mul_f32_e32 v134, v134, v200
	v_mul_f32_e32 v135, v135, v200
	v_mul_f32_e32 v136, v136, v201
	v_mul_f32_e32 v137, v137, v201
	v_mul_f32_e32 v138, v138, v201
	v_mul_f32_e32 v139, v139, v201
	v_mul_f32_e32 v140, v140, v201
	v_mul_f32_e32 v141, v141, v201
	v_mul_f32_e32 v142, v142, v201
	v_mul_f32_e32 v143, v143, v201
	v_mul_f32_e32 v144, v144, v202
	v_mul_f32_e32 v145, v145, v202
	v_mul_f32_e32 v146, v146, v202
	v_mul_f32_e32 v147, v147, v202
	v_mul_f32_e32 v148, v148, v202
	v_mul_f32_e32 v149, v149, v202
	v_mul_f32_e32 v150, v150, v202
	v_mul_f32_e32 v151, v151, v202
	v_mul_f32_e32 v152, v152, v203
	v_mul_f32_e32 v153, v153, v203
	v_mul_f32_e32 v154, v154, v203
	v_mul_f32_e32 v155, v155, v203
	v_mul_f32_e32 v156, v156, v203
	v_mul_f32_e32 v157, v157, v203
	v_mul_f32_e32 v158, v158, v203
	v_mul_f32_e32 v159, v159, v203
	v_cvt_pk_bf16_f32 v204, v128, v129
	v_cvt_pk_bf16_f32 v205, v130, v131
	v_cvt_pk_bf16_f32 v206, v132, v133
	v_cvt_pk_bf16_f32 v207, v134, v135
	v_cvt_pk_bf16_f32 v208, v136, v137
	v_cvt_pk_bf16_f32 v209, v138, v139
	v_cvt_pk_bf16_f32 v210, v140, v141
	v_cvt_pk_bf16_f32 v211, v142, v143
	v_cvt_pk_bf16_f32 v212, v144, v145
	v_cvt_pk_bf16_f32 v213, v146, v147
	v_cvt_pk_bf16_f32 v214, v148, v149
	v_cvt_pk_bf16_f32 v215, v150, v151
	v_cvt_pk_bf16_f32 v216, v152, v153
	v_cvt_pk_bf16_f32 v217, v154, v155
	v_cvt_pk_bf16_f32 v218, v156, v157
	v_cvt_pk_bf16_f32 v219, v158, v159
	global_store_dwordx4 v222, v[204:207], s[16:17]
	global_store_dwordx4 v222, v[208:211], s[16:17] offset:1024
	global_store_dwordx4 v222, v[212:215], s[16:17] offset:2048
	global_store_dwordx4 v222, v[216:219], s[16:17] offset:3072
	s_cmpk_lt_i32 s21, 0x4000
	s_cbranch_scc0 .Lgate0_done
	s_mov_b32 s20, s21
	s_mov_b64 s[16:17], s[14:15]
	s_add_i32 s21, s20, s82
	s_cmpk_lt_i32 s21, 0x4000
	s_cbranch_scc0 .Lgate0_nopfB
	s_lshl_b32 s0, s21, 1
	s_and_b32 s0, s0, 0xffffe000
	s_and_b32 s1, s21, 0xfff
	s_or_b32 s0, s0, s1
	s_mulk_i32 s0, 0x3000
	s_add_u32 s14, s62, s0
	s_addc_u32 s15, s63, 0
	global_load_dwordx4 v[0:3], v221, s[14:15] nt
	global_load_dwordx4 v[16:19], v222, s[14:15] nt
	global_load_dwordx4 v[4:7], v221, s[14:15] offset:1024 nt
	global_load_dwordx4 v[20:23], v222, s[14:15] offset:1024 nt
	global_load_dwordx4 v[8:11], v221, s[14:15] offset:2048 nt
	global_load_dwordx4 v[24:27], v222, s[14:15] offset:2048 nt
	global_load_dwordx4 v[12:15], v221, s[14:15] offset:3072 nt
	global_load_dwordx4 v[28:31], v222, s[14:15] offset:3072 nt
	s_waitcnt vmcnt(12)
	s_branch .Lgate0_goB

.Lgate0_goB:
	v_lshlrev_b32_e32 v96, 16, v48
	v_and_b32_e32 v97, 0xffff0000, v48
	v_lshlrev_b32_e32 v98, 16, v49
	v_and_b32_e32 v99, 0xffff0000, v49
	v_lshlrev_b32_e32 v100, 16, v50
	v_and_b32_e32 v101, 0xffff0000, v50
	v_lshlrev_b32_e32 v102, 16, v51
	v_and_b32_e32 v103, 0xffff0000, v51
	v_mul_f32_e32 v192, v96, v96
	v_fmac_f32_e32 v192, v97, v97
	v_fmac_f32_e32 v192, v98, v98
	v_fmac_f32_e32 v192, v99, v99
	v_fmac_f32_e32 v192, v100, v100
	v_fmac_f32_e32 v192, v101, v101
	v_fmac_f32_e32 v192, v102, v102
	v_fmac_f32_e32 v192, v103, v103
	v_lshlrev_b32_e32 v104, 16, v52
	v_and_b32_e32 v105, 0xffff0000, v52
	v_lshlrev_b32_e32 v106, 16, v53
	v_and_b32_e32 v107, 0xffff0000, v53
	v_lshlrev_b32_e32 v108, 16, v54
	v_and_b32_e32 v109, 0xffff0000, v54
	v_lshlrev_b32_e32 v110, 16, v55
	v_and_b32_e32 v111, 0xffff0000, v55
	v_mul_f32_e32 v193, v104, v104
	v_fmac_f32_e32 v193, v105, v105
	v_fmac_f32_e32 v193, v106, v106
	v_fmac_f32_e32 v193, v107, v107
	v_fmac_f32_e32 v193, v108, v108
	v_fmac_f32_e32 v193, v109, v109
	v_fmac_f32_e32 v193, v110, v110
	v_fmac_f32_e32 v193, v111, v111
	v_lshlrev_b32_e32 v112, 16, v56
	v_and_b32_e32 v113, 0xffff0000, v56
	v_lshlrev_b32_e32 v114, 16, v57
	v_and_b32_e32 v115, 0xffff0000, v57
	v_lshlrev_b32_e32 v116, 16, v58
	v_and_b32_e32 v117, 0xffff0000, v58
	v_lshlrev_b32_e32 v118, 16, v59
	v_and_b32_e32 v119, 0xffff0000, v59
	v_mul_f32_e32 v194, v112, v112
	v_fmac_f32_e32 v194, v113, v113
	v_fmac_f32_e32 v194, v114, v114
	v_fmac_f32_e32 v194, v115, v115
	v_fmac_f32_e32 v194, v116, v116
	v_fmac_f32_e32 v194, v117, v117
	v_fmac_f32_e32 v194, v118, v118
	v_fmac_f32_e32 v194, v119, v119
	v_lshlrev_b32_e32 v120, 16, v60
	v_and_b32_e32 v121, 0xffff0000, v60
	v_lshlrev_b32_e32 v122, 16, v61
	v_and_b32_e32 v123, 0xffff0000, v61
	v_lshlrev_b32_e32 v124, 16, v62
	v_and_b32_e32 v125, 0xffff0000, v62
	v_lshlrev_b32_e32 v126, 16, v63
	v_and_b32_e32 v127, 0xffff0000, v63
	v_mul_f32_e32 v195, v120, v120
	v_fmac_f32_e32 v195, v121, v121
	v_fmac_f32_e32 v195, v122, v122
	v_fmac_f32_e32 v195, v123, v123
	v_fmac_f32_e32 v195, v124, v124
	v_fmac_f32_e32 v195, v125, v125
	v_fmac_f32_e32 v195, v126, v126
	v_fmac_f32_e32 v195, v127, v127
	s_nop 1
	v_add_f32_dpp v196, v192, v192 quad_perm:[1,0,3,2] row_mask:0xf bank_mask:0xf
	v_add_f32_dpp v197, v193, v193 quad_perm:[1,0,3,2] row_mask:0xf bank_mask:0xf
	v_add_f32_dpp v198, v194, v194 quad_perm:[1,0,3,2] row_mask:0xf bank_mask:0xf
	v_add_f32_dpp v199, v195, v195 quad_perm:[1,0,3,2] row_mask:0xf bank_mask:0xf
	v_add_f32_dpp v192, v196, v196 quad_perm:[2,3,0,1] row_mask:0xf bank_mask:0xf
	v_add_f32_dpp v193, v197, v197 quad_perm:[2,3,0,1] row_mask:0xf bank_mask:0xf
	v_add_f32_dpp v194, v198, v198 quad_perm:[2,3,0,1] row_mask:0xf bank_mask:0xf
	v_add_f32_dpp v195, v199, v199 quad_perm:[2,3,0,1] row_mask:0xf bank_mask:0xf
	v_add_f32_dpp v196, v192, v192 row_half_mirror row_mask:0xf bank_mask:0xf
	v_add_f32_dpp v197, v193, v193 row_half_mirror row_mask:0xf bank_mask:0xf
	v_add_f32_dpp v198, v194, v194 row_half_mirror row_mask:0xf bank_mask:0xf
	v_add_f32_dpp v199, v195, v195 row_half_mirror row_mask:0xf bank_mask:0xf
	v_add_f32_dpp v192, v196, v196 row_mirror row_mask:0xf bank_mask:0xf
	v_add_f32_dpp v193, v197, v197 row_mirror row_mask:0xf bank_mask:0xf
	v_add_f32_dpp v194, v198, v198 row_mirror row_mask:0xf bank_mask:0xf
	v_add_f32_dpp v195, v199, v199 row_mirror row_mask:0xf bank_mask:0xf
	s_nop 0
	v_readlane_b32 s0, v192, 0
	v_readlane_b32 s1, v192, 16
	v_readlane_b32 s6, v192, 32
	v_readlane_b32 s7, v192, 48
	s_nop 1
	v_mov_b32_e32 v196, s0
	v_add_f32_e32 v196, s1, v196
	v_add_f32_e32 v196, s6, v196
	v_add_f32_e32 v196, s7, v196
	v_fmamk_f32 v196, v196, 0x3b000000, v223
	v_readlane_b32 s0, v193, 0
	v_readlane_b32 s1, v193, 16
	v_readlane_b32 s6, v193, 32
	v_readlane_b32 s7, v193, 48
	s_nop 1
	v_mov_b32_e32 v197, s0
	v_add_f32_e32 v197, s1, v197
	v_add_f32_e32 v197, s6, v197
	v_add_f32_e32 v197, s7, v197
	v_fmamk_f32 v197, v197, 0x3b000000, v223
	v_readlane_b32 s0, v194, 0
	v_readlane_b32 s1, v194, 16
	v_readlane_b32 s6, v194, 32
	v_readlane_b32 s7, v194, 48
	s_nop 1
	v_mov_b32_e32 v198, s0
	v_add_f32_e32 v198, s1, v198
	v_add_f32_e32 v198, s6, v198
	v_add_f32_e32 v198, s7, v198
	v_fmamk_f32 v198, v198, 0x3b000000, v223
	v_readlane_b32 s0, v195, 0
	v_readlane_b32 s1, v195, 16
	v_readlane_b32 s6, v195, 32
	v_readlane_b32 s7, v195, 48
	s_nop 1
	v_mov_b32_e32 v199, s0
	v_add_f32_e32 v199, s1, v199
	v_add_f32_e32 v199, s6, v199
	v_add_f32_e32 v199, s7, v199
	v_fmamk_f32 v199, v199, 0x3b000000, v223
	v_rsq_f32_e32 v200, v196
	v_rsq_f32_e32 v201, v197
	v_rsq_f32_e32 v202, v198
	v_rsq_f32_e32 v203, v199
	v_lshlrev_b32_e32 v128, 16, v64
	v_and_b32_e32 v129, 0xffff0000, v64
	v_lshlrev_b32_e32 v130, 16, v65
	v_and_b32_e32 v131, 0xffff0000, v65
	v_lshlrev_b32_e32 v132, 16, v66
	v_and_b32_e32 v133, 0xffff0000, v66
	v_lshlrev_b32_e32 v134, 16, v67
	v_and_b32_e32 v135, 0xffff0000, v67
	v_lshlrev_b32_e32 v136, 16, v68
	v_and_b32_e32 v137, 0xffff0000, v68
	v_lshlrev_b32_e32 v138, 16, v69
	v_and_b32_e32 v139, 0xffff0000, v69
	v_lshlrev_b32_e32 v140, 16, v70
	v_and_b32_e32 v141, 0xffff0000, v70
	v_lshlrev_b32_e32 v142, 16, v71
	v_and_b32_e32 v143, 0xffff0000, v71
	v_lshlrev_b32_e32 v144, 16, v72
	v_and_b32_e32 v145, 0xffff0000, v72
	v_lshlrev_b32_e32 v146, 16, v73
	v_and_b32_e32 v147, 0xffff0000, v73
	v_lshlrev_b32_e32 v148, 16, v74
	v_and_b32_e32 v149, 0xffff0000, v74
	v_lshlrev_b32_e32 v150, 16, v75
	v_and_b32_e32 v151, 0xffff0000, v75
	v_lshlrev_b32_e32 v152, 16, v76
	v_and_b32_e32 v153, 0xffff0000, v76
	v_lshlrev_b32_e32 v154, 16, v77
	v_and_b32_e32 v155, 0xffff0000, v77
	v_lshlrev_b32_e32 v156, 16, v78
	v_and_b32_e32 v157, 0xffff0000, v78
	v_lshlrev_b32_e32 v158, 16, v79
	v_and_b32_e32 v159, 0xffff0000, v79
	v_mul_f32_e32 v160, 0xbfb8aa3b, v128
	v_mul_f32_e32 v161, 0xbfb8aa3b, v129
	v_mul_f32_e32 v162, 0xbfb8aa3b, v130
	v_mul_f32_e32 v163, 0xbfb8aa3b, v131
	v_mul_f32_e32 v164, 0xbfb8aa3b, v132
	v_mul_f32_e32 v165, 0xbfb8aa3b, v133
	v_mul_f32_e32 v166, 0xbfb8aa3b, v134
	v_mul_f32_e32 v167, 0xbfb8aa3b, v135
	v_mul_f32_e32 v168, 0xbfb8aa3b, v136
	v_mul_f32_e32 v169, 0xbfb8aa3b, v137
	v_mul_f32_e32 v170, 0xbfb8aa3b, v138
	v_mul_f32_e32 v171, 0xbfb8aa3b, v139
	v_mul_f32_e32 v172, 0xbfb8aa3b, v140
	v_mul_f32_e32 v173, 0xbfb8aa3b, v141
	v_mul_f32_e32 v174, 0xbfb8aa3b, v142
	v_mul_f32_e32 v175, 0xbfb8aa3b, v143
	v_mul_f32_e32 v176, 0xbfb8aa3b, v144
	v_mul_f32_e32 v177, 0xbfb8aa3b, v145
	v_mul_f32_e32 v178, 0xbfb8aa3b, v146
	v_mul_f32_e32 v179, 0xbfb8aa3b, v147
	v_mul_f32_e32 v180, 0xbfb8aa3b, v148
	v_mul_f32_e32 v181, 0xbfb8aa3b, v149
	v_mul_f32_e32 v182, 0xbfb8aa3b, v150
	v_mul_f32_e32 v183, 0xbfb8aa3b, v151
	v_mul_f32_e32 v184, 0xbfb8aa3b, v152
	v_mul_f32_e32 v185, 0xbfb8aa3b, v153
	v_mul_f32_e32 v186, 0xbfb8aa3b, v154
	v_mul_f32_e32 v187, 0xbfb8aa3b, v155
	v_mul_f32_e32 v188, 0xbfb8aa3b, v156
	v_mul_f32_e32 v189, 0xbfb8aa3b, v157
	v_mul_f32_e32 v190, 0xbfb8aa3b, v158
	v_mul_f32_e32 v191, 0xbfb8aa3b, v159
	v_exp_f32_e32 v160, v160
	v_exp_f32_e32 v161, v161
	v_exp_f32_e32 v162, v162
	v_exp_f32_e32 v163, v163
	v_exp_f32_e32 v164, v164
	v_exp_f32_e32 v165, v165
	v_exp_f32_e32 v166, v166
	v_exp_f32_e32 v167, v167
	v_exp_f32_e32 v168, v168
	v_exp_f32_e32 v169, v169
	v_exp_f32_e32 v170, v170
	v_exp_f32_e32 v171, v171
	v_exp_f32_e32 v172, v172
	v_exp_f32_e32 v173, v173
	v_exp_f32_e32 v174, v174
	v_exp_f32_e32 v175, v175
	v_exp_f32_e32 v176, v176
	v_exp_f32_e32 v177, v177
	v_exp_f32_e32 v178, v178
	v_exp_f32_e32 v179, v179
	v_exp_f32_e32 v180, v180
	v_exp_f32_e32 v181, v181
	v_exp_f32_e32 v182, v182
	v_exp_f32_e32 v183, v183
	v_exp_f32_e32 v184, v184
	v_exp_f32_e32 v185, v185
	v_exp_f32_e32 v186, v186
	v_exp_f32_e32 v187, v187
	v_exp_f32_e32 v188, v188
	v_exp_f32_e32 v189, v189
	v_exp_f32_e32 v190, v190
	v_exp_f32_e32 v191, v191
	v_add_f32_e32 v160, 1.0, v160
	v_add_f32_e32 v161, 1.0, v161
	v_add_f32_e32 v162, 1.0, v162
	v_add_f32_e32 v163, 1.0, v163
	v_add_f32_e32 v164, 1.0, v164
	v_add_f32_e32 v165, 1.0, v165
	v_add_f32_e32 v166, 1.0, v166
	v_add_f32_e32 v167, 1.0, v167
	v_add_f32_e32 v168, 1.0, v168
	v_add_f32_e32 v169, 1.0, v169
	v_add_f32_e32 v170, 1.0, v170
	v_add_f32_e32 v171, 1.0, v171
	v_add_f32_e32 v172, 1.0, v172
	v_add_f32_e32 v173, 1.0, v173
	v_add_f32_e32 v174, 1.0, v174
	v_add_f32_e32 v175, 1.0, v175
	v_add_f32_e32 v176, 1.0, v176
	v_add_f32_e32 v177, 1.0, v177
	v_add_f32_e32 v178, 1.0, v178
	v_add_f32_e32 v179, 1.0, v179
	v_add_f32_e32 v180, 1.0, v180
	v_add_f32_e32 v181, 1.0, v181
	v_add_f32_e32 v182, 1.0, v182
	v_add_f32_e32 v183, 1.0, v183
	v_add_f32_e32 v184, 1.0, v184
	v_add_f32_e32 v185, 1.0, v185
	v_add_f32_e32 v186, 1.0, v186
	v_add_f32_e32 v187, 1.0, v187
	v_add_f32_e32 v188, 1.0, v188
	v_add_f32_e32 v189, 1.0, v189
	v_add_f32_e32 v190, 1.0, v190
	v_add_f32_e32 v191, 1.0, v191
	v_rcp_f32_e32 v160, v160
	v_rcp_f32_e32 v161, v161
	v_rcp_f32_e32 v162, v162
	v_rcp_f32_e32 v163, v163
	v_rcp_f32_e32 v164, v164
	v_rcp_f32_e32 v165, v165
	v_rcp_f32_e32 v166, v166
	v_rcp_f32_e32 v167, v167
	v_rcp_f32_e32 v168, v168
	v_rcp_f32_e32 v169, v169
	v_rcp_f32_e32 v170, v170
	v_rcp_f32_e32 v171, v171
	v_rcp_f32_e32 v172, v172
	v_rcp_f32_e32 v173, v173
	v_rcp_f32_e32 v174, v174
	v_rcp_f32_e32 v175, v175
	v_rcp_f32_e32 v176, v176
	v_rcp_f32_e32 v177, v177
	v_rcp_f32_e32 v178, v178
	v_rcp_f32_e32 v179, v179
	v_rcp_f32_e32 v180, v180
	v_rcp_f32_e32 v181, v181
	v_rcp_f32_e32 v182, v182
	v_rcp_f32_e32 v183, v183
	v_rcp_f32_e32 v184, v184
	v_rcp_f32_e32 v185, v185
	v_rcp_f32_e32 v186, v186
	v_rcp_f32_e32 v187, v187
	v_rcp_f32_e32 v188, v188
	v_rcp_f32_e32 v189, v189
	v_rcp_f32_e32 v190, v190
	v_rcp_f32_e32 v191, v191
	v_mul_f32_e32 v128, v160, v128
	v_mul_f32_e32 v129, v161, v129
	v_mul_f32_e32 v130, v162, v130
	v_mul_f32_e32 v131, v163, v131
	v_mul_f32_e32 v132, v164, v132
	v_mul_f32_e32 v133, v165, v133
	v_mul_f32_e32 v134, v166, v134
	v_mul_f32_e32 v135, v167, v135
	v_mul_f32_e32 v136, v168, v136
	v_mul_f32_e32 v137, v169, v137
	v_mul_f32_e32 v138, v170, v138
	v_mul_f32_e32 v139, v171, v139
	v_mul_f32_e32 v140, v172, v140
	v_mul_f32_e32 v141, v173, v141
	v_mul_f32_e32 v142, v174, v142
	v_mul_f32_e32 v143, v175, v143
	v_mul_f32_e32 v144, v176, v144
	v_mul_f32_e32 v145, v177, v145
	v_mul_f32_e32 v146, v178, v146
	v_mul_f32_e32 v147, v179, v147
	v_mul_f32_e32 v148, v180, v148
	v_mul_f32_e32 v149, v181, v149
	v_mul_f32_e32 v150, v182, v150
	v_mul_f32_e32 v151, v183, v151
	v_mul_f32_e32 v152, v184, v152
	v_mul_f32_e32 v153, v185, v153
	v_mul_f32_e32 v154, v186, v154
	v_mul_f32_e32 v155, v187, v155
	v_mul_f32_e32 v156, v188, v156
	v_mul_f32_e32 v157, v189, v157
	v_mul_f32_e32 v158, v190, v158
	v_mul_f32_e32 v159, v191, v159
	v_mul_f32_e32 v128, v128, v96
	v_mul_f32_e32 v129, v129, v97
	v_mul_f32_e32 v130, v130, v98
	v_mul_f32_e32 v131, v131, v99
	v_mul_f32_e32 v132, v132, v100
	v_mul_f32_e32 v133, v133, v101
	v_mul_f32_e32 v134, v134, v102
	v_mul_f32_e32 v135, v135, v103
	v_mul_f32_e32 v136, v136, v104
	v_mul_f32_e32 v137, v137, v105
	v_mul_f32_e32 v138, v138, v106
	v_mul_f32_e32 v139, v139, v107
	v_mul_f32_e32 v140, v140, v108
	v_mul_f32_e32 v141, v141, v109
	v_mul_f32_e32 v142, v142, v110
	v_mul_f32_e32 v143, v143, v111
	v_mul_f32_e32 v144, v144, v112
	v_mul_f32_e32 v145, v145, v113
	v_mul_f32_e32 v146, v146, v114
	v_mul_f32_e32 v147, v147, v115
	v_mul_f32_e32 v148, v148, v116
	v_mul_f32_e32 v149, v149, v117
	v_mul_f32_e32 v150, v150, v118
	v_mul_f32_e32 v151, v151, v119
	v_mul_f32_e32 v152, v152, v120
	v_mul_f32_e32 v153, v153, v121
	v_mul_f32_e32 v154, v154, v122
	v_mul_f32_e32 v155, v155, v123
	v_mul_f32_e32 v156, v156, v124
	v_mul_f32_e32 v157, v157, v125
	v_mul_f32_e32 v158, v158, v126
	v_mul_f32_e32 v159, v159, v127
	v_mul_f32_e32 v128, v128, v200
	v_mul_f32_e32 v129, v129, v200
	v_mul_f32_e32 v130, v130, v200
	v_mul_f32_e32 v131, v131, v200
	v_mul_f32_e32 v132, v132, v200
	v_mul_f32_e32 v133, v133, v200
	v_mul_f32_e32 v134, v134, v200
	v_mul_f32_e32 v135, v135, v200
	v_mul_f32_e32 v136, v136, v201
	v_mul_f32_e32 v137, v137, v201
	v_mul_f32_e32 v138, v138, v201
	v_mul_f32_e32 v139, v139, v201
	v_mul_f32_e32 v140, v140, v201
	v_mul_f32_e32 v141, v141, v201
	v_mul_f32_e32 v142, v142, v201
	v_mul_f32_e32 v143, v143, v201
	v_mul_f32_e32 v144, v144, v202
	v_mul_f32_e32 v145, v145, v202
	v_mul_f32_e32 v146, v146, v202
	v_mul_f32_e32 v147, v147, v202
	v_mul_f32_e32 v148, v148, v202
	v_mul_f32_e32 v149, v149, v202
	v_mul_f32_e32 v150, v150, v202
	v_mul_f32_e32 v151, v151, v202
	v_mul_f32_e32 v152, v152, v203
	v_mul_f32_e32 v153, v153, v203
	v_mul_f32_e32 v154, v154, v203
	v_mul_f32_e32 v155, v155, v203
	v_mul_f32_e32 v156, v156, v203
	v_mul_f32_e32 v157, v157, v203
	v_mul_f32_e32 v158, v158, v203
	v_mul_f32_e32 v159, v159, v203
	v_cvt_pk_bf16_f32 v204, v128, v129
	v_cvt_pk_bf16_f32 v205, v130, v131
	v_cvt_pk_bf16_f32 v206, v132, v133
	v_cvt_pk_bf16_f32 v207, v134, v135
	v_cvt_pk_bf16_f32 v208, v136, v137
	v_cvt_pk_bf16_f32 v209, v138, v139
	v_cvt_pk_bf16_f32 v210, v140, v141
	v_cvt_pk_bf16_f32 v211, v142, v143
	v_cvt_pk_bf16_f32 v212, v144, v145
	v_cvt_pk_bf16_f32 v213, v146, v147
	v_cvt_pk_bf16_f32 v214, v148, v149
	v_cvt_pk_bf16_f32 v215, v150, v151
	v_cvt_pk_bf16_f32 v216, v152, v153
	v_cvt_pk_bf16_f32 v217, v154, v155
	v_cvt_pk_bf16_f32 v218, v156, v157
	v_cvt_pk_bf16_f32 v219, v158, v159
	global_store_dwordx4 v222, v[204:207], s[16:17]
	global_store_dwordx4 v222, v[208:211], s[16:17] offset:1024
	global_store_dwordx4 v222, v[212:215], s[16:17] offset:2048
	global_store_dwordx4 v222, v[216:219], s[16:17] offset:3072
	s_cmpk_lt_i32 s21, 0x4000
	s_cbranch_scc0 .Lgate0_done
	s_mov_b32 s20, s21
	s_mov_b64 s[16:17], s[14:15]
	s_branch .Lgate0_topA

.Lgate1_goA:
	v_lshlrev_b32_e32 v96, 16, v0
	v_and_b32_e32 v97, 0xffff0000, v0
	v_lshlrev_b32_e32 v160, 16, v32
	v_and_b32_e32 v161, 0xffff0000, v32
	v_lshlrev_b32_e32 v98, 16, v1
	v_and_b32_e32 v99, 0xffff0000, v1
	v_lshlrev_b32_e32 v162, 16, v33
	v_and_b32_e32 v163, 0xffff0000, v33
	v_lshlrev_b32_e32 v100, 16, v2
	v_and_b32_e32 v101, 0xffff0000, v2
	v_lshlrev_b32_e32 v164, 16, v34
	v_and_b32_e32 v165, 0xffff0000, v34
	v_lshlrev_b32_e32 v102, 16, v3
	v_and_b32_e32 v103, 0xffff0000, v3
	v_lshlrev_b32_e32 v166, 16, v35
	v_and_b32_e32 v167, 0xffff0000, v35
	v_add_f32_e32 v96, v96, v160
	v_add_f32_e32 v97, v97, v161
	v_add_f32_e32 v98, v98, v162
	v_add_f32_e32 v99, v99, v163
	v_add_f32_e32 v100, v100, v164
	v_add_f32_e32 v101, v101, v165
	v_add_f32_e32 v102, v102, v166
	v_add_f32_e32 v103, v103, v167
	v_cvt_pk_bf16_f32 v160, v96, v97
	v_cvt_pk_bf16_f32 v161, v98, v99
	v_cvt_pk_bf16_f32 v162, v100, v101
	v_cvt_pk_bf16_f32 v163, v102, v103
	v_lshlrev_b32_e32 v96, 16, v160
	v_and_b32_e32 v97, 0xffff0000, v160
	v_lshlrev_b32_e32 v98, 16, v161
	v_and_b32_e32 v99, 0xffff0000, v161
	v_lshlrev_b32_e32 v100, 16, v162
	v_and_b32_e32 v101, 0xffff0000, v162
	v_lshlrev_b32_e32 v102, 16, v163
	v_and_b32_e32 v103, 0xffff0000, v163
	v_mul_f32_e32 v192, v96, v96
	v_fmac_f32_e32 v192, v97, v97
	v_fmac_f32_e32 v192, v98, v98
	v_fmac_f32_e32 v192, v99, v99
	v_fmac_f32_e32 v192, v100, v100
	v_fmac_f32_e32 v192, v101, v101
	v_fmac_f32_e32 v192, v102, v102
	v_fmac_f32_e32 v192, v103, v103
	v_lshlrev_b32_e32 v104, 16, v4
	v_and_b32_e32 v105, 0xffff0000, v4
	v_lshlrev_b32_e32 v168, 16, v36
	v_and_b32_e32 v169, 0xffff0000, v36
	v_lshlrev_b32_e32 v106, 16, v5
	v_and_b32_e32 v107, 0xffff0000, v5
	v_lshlrev_b32_e32 v170, 16, v37
	v_and_b32_e32 v171, 0xffff0000, v37
	v_lshlrev_b32_e32 v108, 16, v6
	v_and_b32_e32 v109, 0xffff0000, v6
	v_lshlrev_b32_e32 v172, 16, v38
	v_and_b32_e32 v173, 0xffff0000, v38
	v_lshlrev_b32_e32 v110, 16, v7
	v_and_b32_e32 v111, 0xffff0000, v7
	v_lshlrev_b32_e32 v174, 16, v39
	v_and_b32_e32 v175, 0xffff0000, v39
	v_add_f32_e32 v104, v104, v168
	v_add_f32_e32 v105, v105, v169
	v_add_f32_e32 v106, v106, v170
	v_add_f32_e32 v107, v107, v171
	v_add_f32_e32 v108, v108, v172
	v_add_f32_e32 v109, v109, v173
	v_add_f32_e32 v110, v110, v174
	v_add_f32_e32 v111, v111, v175
	v_cvt_pk_bf16_f32 v168, v104, v105
	v_cvt_pk_bf16_f32 v169, v106, v107
	v_cvt_pk_bf16_f32 v170, v108, v109
	v_cvt_pk_bf16_f32 v171, v110, v111
	v_lshlrev_b32_e32 v104, 16, v168
	v_and_b32_e32 v105, 0xffff0000, v168
	v_lshlrev_b32_e32 v106, 16, v169
	v_and_b32_e32 v107, 0xffff0000, v169
	v_lshlrev_b32_e32 v108, 16, v170
	v_and_b32_e32 v109, 0xffff0000, v170
	v_lshlrev_b32_e32 v110, 16, v171
	v_and_b32_e32 v111, 0xffff0000, v171
	v_mul_f32_e32 v193, v104, v104
	v_fmac_f32_e32 v193, v105, v105
	v_fmac_f32_e32 v193, v106, v106
	v_fmac_f32_e32 v193, v107, v107
	v_fmac_f32_e32 v193, v108, v108
	v_fmac_f32_e32 v193, v109, v109
	v_fmac_f32_e32 v193, v110, v110
	v_fmac_f32_e32 v193, v111, v111
	v_lshlrev_b32_e32 v112, 16, v8
	v_and_b32_e32 v113, 0xffff0000, v8
	v_lshlrev_b32_e32 v176, 16, v40
	v_and_b32_e32 v177, 0xffff0000, v40
	v_lshlrev_b32_e32 v114, 16, v9
	v_and_b32_e32 v115, 0xffff0000, v9
	v_lshlrev_b32_e32 v178, 16, v41
	v_and_b32_e32 v179, 0xffff0000, v41
	v_lshlrev_b32_e32 v116, 16, v10
	v_and_b32_e32 v117, 0xffff0000, v10
	v_lshlrev_b32_e32 v180, 16, v42
	v_and_b32_e32 v181, 0xffff0000, v42
	v_lshlrev_b32_e32 v118, 16, v11
	v_and_b32_e32 v119, 0xffff0000, v11
	v_lshlrev_b32_e32 v182, 16, v43
	v_and_b32_e32 v183, 0xffff0000, v43
	v_add_f32_e32 v112, v112, v176
	v_add_f32_e32 v113, v113, v177
	v_add_f32_e32 v114, v114, v178
	v_add_f32_e32 v115, v115, v179
	v_add_f32_e32 v116, v116, v180
	v_add_f32_e32 v117, v117, v181
	v_add_f32_e32 v118, v118, v182
	v_add_f32_e32 v119, v119, v183
	v_cvt_pk_bf16_f32 v176, v112, v113
	v_cvt_pk_bf16_f32 v177, v114, v115
	v_cvt_pk_bf16_f32 v178, v116, v117
	v_cvt_pk_bf16_f32 v179, v118, v119
	v_lshlrev_b32_e32 v112, 16, v176
	v_and_b32_e32 v113, 0xffff0000, v176
	v_lshlrev_b32_e32 v114, 16, v177
	v_and_b32_e32 v115, 0xffff0000, v177
	v_lshlrev_b32_e32 v116, 16, v178
	v_and_b32_e32 v117, 0xffff0000, v178
	v_lshlrev_b32_e32 v118, 16, v179
	v_and_b32_e32 v119, 0xffff0000, v179
	v_mul_f32_e32 v194, v112, v112
	v_fmac_f32_e32 v194, v113, v113
	v_fmac_f32_e32 v194, v114, v114
	v_fmac_f32_e32 v194, v115, v115
	v_fmac_f32_e32 v194, v116, v116
	v_fmac_f32_e32 v194, v117, v117
	v_fmac_f32_e32 v194, v118, v118
	v_fmac_f32_e32 v194, v119, v119
	v_lshlrev_b32_e32 v120, 16, v12
	v_and_b32_e32 v121, 0xffff0000, v12
	v_lshlrev_b32_e32 v184, 16, v44
	v_and_b32_e32 v185, 0xffff0000, v44
	v_lshlrev_b32_e32 v122, 16, v13
	v_and_b32_e32 v123, 0xffff0000, v13
	v_lshlrev_b32_e32 v186, 16, v45
	v_and_b32_e32 v187, 0xffff0000, v45
	v_lshlrev_b32_e32 v124, 16, v14
	v_and_b32_e32 v125, 0xffff0000, v14
	v_lshlrev_b32_e32 v188, 16, v46
	v_and_b32_e32 v189, 0xffff0000, v46
	v_lshlrev_b32_e32 v126, 16, v15
	v_and_b32_e32 v127, 0xffff0000, v15
	v_lshlrev_b32_e32 v190, 16, v47
	v_and_b32_e32 v191, 0xffff0000, v47
	v_add_f32_e32 v120, v120, v184
	v_add_f32_e32 v121, v121, v185
	v_add_f32_e32 v122, v122, v186
	v_add_f32_e32 v123, v123, v187
	v_add_f32_e32 v124, v124, v188
	v_add_f32_e32 v125, v125, v189
	v_add_f32_e32 v126, v126, v190
	v_add_f32_e32 v127, v127, v191
	v_cvt_pk_bf16_f32 v184, v120, v121
	v_cvt_pk_bf16_f32 v185, v122, v123
	v_cvt_pk_bf16_f32 v186, v124, v125
	v_cvt_pk_bf16_f32 v187, v126, v127
	v_lshlrev_b32_e32 v120, 16, v184
	v_and_b32_e32 v121, 0xffff0000, v184
	v_lshlrev_b32_e32 v122, 16, v185
	v_and_b32_e32 v123, 0xffff0000, v185
	v_lshlrev_b32_e32 v124, 16, v186
	v_and_b32_e32 v125, 0xffff0000, v186
	v_lshlrev_b32_e32 v126, 16, v187
	v_and_b32_e32 v127, 0xffff0000, v187
	v_mul_f32_e32 v195, v120, v120
	v_fmac_f32_e32 v195, v121, v121
	v_fmac_f32_e32 v195, v122, v122
	v_fmac_f32_e32 v195, v123, v123
	v_fmac_f32_e32 v195, v124, v124
	v_fmac_f32_e32 v195, v125, v125
	v_fmac_f32_e32 v195, v126, v126
	v_fmac_f32_e32 v195, v127, v127
	s_nop 1
	v_add_f32_dpp v196, v192, v192 quad_perm:[1,0,3,2] row_mask:0xf bank_mask:0xf
	v_add_f32_dpp v197, v193, v193 quad_perm:[1,0,3,2] row_mask:0xf bank_mask:0xf
	v_add_f32_dpp v198, v194, v194 quad_perm:[1,0,3,2] row_mask:0xf bank_mask:0xf
	v_add_f32_dpp v199, v195, v195 quad_perm:[1,0,3,2] row_mask:0xf bank_mask:0xf
	v_add_f32_dpp v192, v196, v196 quad_perm:[2,3,0,1] row_mask:0xf bank_mask:0xf
	v_add_f32_dpp v193, v197, v197 quad_perm:[2,3,0,1] row_mask:0xf bank_mask:0xf
	v_add_f32_dpp v194, v198, v198 quad_perm:[2,3,0,1] row_mask:0xf bank_mask:0xf
	v_add_f32_dpp v195, v199, v199 quad_perm:[2,3,0,1] row_mask:0xf bank_mask:0xf
	v_add_f32_dpp v196, v192, v192 row_half_mirror row_mask:0xf bank_mask:0xf
	v_add_f32_dpp v197, v193, v193 row_half_mirror row_mask:0xf bank_mask:0xf
	v_add_f32_dpp v198, v194, v194 row_half_mirror row_mask:0xf bank_mask:0xf
	v_add_f32_dpp v199, v195, v195 row_half_mirror row_mask:0xf bank_mask:0xf
	v_add_f32_dpp v192, v196, v196 row_mirror row_mask:0xf bank_mask:0xf
	v_add_f32_dpp v193, v197, v197 row_mirror row_mask:0xf bank_mask:0xf
	v_add_f32_dpp v194, v198, v198 row_mirror row_mask:0xf bank_mask:0xf
	v_add_f32_dpp v195, v199, v199 row_mirror row_mask:0xf bank_mask:0xf
	s_nop 0
	v_readlane_b32 s0, v192, 0
	v_readlane_b32 s1, v192, 16
	v_readlane_b32 s6, v192, 32
	v_readlane_b32 s7, v192, 48
	s_nop 1
	v_mov_b32_e32 v196, s0
	v_add_f32_e32 v196, s1, v196
	v_add_f32_e32 v196, s6, v196
	v_add_f32_e32 v196, s7, v196
	v_fmamk_f32 v196, v196, 0x3b000000, v223
	v_readlane_b32 s0, v193, 0
	v_readlane_b32 s1, v193, 16
	v_readlane_b32 s6, v193, 32
	v_readlane_b32 s7, v193, 48
	s_nop 1
	v_mov_b32_e32 v197, s0
	v_add_f32_e32 v197, s1, v197
	v_add_f32_e32 v197, s6, v197
	v_add_f32_e32 v197, s7, v197
	v_fmamk_f32 v197, v197, 0x3b000000, v223
	v_readlane_b32 s0, v194, 0
	v_readlane_b32 s1, v194, 16
	v_readlane_b32 s6, v194, 32
	v_readlane_b32 s7, v194, 48
	s_nop 1
	v_mov_b32_e32 v198, s0
	v_add_f32_e32 v198, s1, v198
	v_add_f32_e32 v198, s6, v198
	v_add_f32_e32 v198, s7, v198
	v_fmamk_f32 v198, v198, 0x3b000000, v223
	v_readlane_b32 s0, v195, 0
	v_readlane_b32 s1, v195, 16
	v_readlane_b32 s6, v195, 32
	v_readlane_b32 s7, v195, 48
	s_nop 1
	v_mov_b32_e32 v199, s0
	v_add_f32_e32 v199, s1, v199
	v_add_f32_e32 v199, s6, v199
	v_add_f32_e32 v199, s7, v199
	v_fmamk_f32 v199, v199, 0x3b000000, v223
	v_rsq_f32_e32 v200, v196
	v_rsq_f32_e32 v201, v197
	v_rsq_f32_e32 v202, v198
	v_rsq_f32_e32 v203, v199
	v_lshlrev_b32_e32 v128, 16, v16
	v_and_b32_e32 v129, 0xffff0000, v16
	v_lshlrev_b32_e32 v130, 16, v17
	v_and_b32_e32 v131, 0xffff0000, v17
	v_lshlrev_b32_e32 v132, 16, v18
	v_and_b32_e32 v133, 0xffff0000, v18
	v_lshlrev_b32_e32 v134, 16, v19
	v_and_b32_e32 v135, 0xffff0000, v19
	v_lshlrev_b32_e32 v136, 16, v20
	v_and_b32_e32 v137, 0xffff0000, v20
	v_lshlrev_b32_e32 v138, 16, v21
	v_and_b32_e32 v139, 0xffff0000, v21
	v_lshlrev_b32_e32 v140, 16, v22
	v_and_b32_e32 v141, 0xffff0000, v22
	v_lshlrev_b32_e32 v142, 16, v23
	v_and_b32_e32 v143, 0xffff0000, v23
	v_lshlrev_b32_e32 v144, 16, v24
	v_and_b32_e32 v145, 0xffff0000, v24
	v_lshlrev_b32_e32 v146, 16, v25
	v_and_b32_e32 v147, 0xffff0000, v25
	v_lshlrev_b32_e32 v148, 16, v26
	v_and_b32_e32 v149, 0xffff0000, v26
	v_lshlrev_b32_e32 v150, 16, v27
	v_and_b32_e32 v151, 0xffff0000, v27
	v_lshlrev_b32_e32 v152, 16, v28
	v_and_b32_e32 v153, 0xffff0000, v28
	v_lshlrev_b32_e32 v154, 16, v29
	v_and_b32_e32 v155, 0xffff0000, v29
	v_lshlrev_b32_e32 v156, 16, v30
	v_and_b32_e32 v157, 0xffff0000, v30
	v_lshlrev_b32_e32 v158, 16, v31
	v_and_b32_e32 v159, 0xffff0000, v31
	v_mul_f32_e32 v160, 0xbfb8aa3b, v128
	v_mul_f32_e32 v161, 0xbfb8aa3b, v129
	v_mul_f32_e32 v162, 0xbfb8aa3b, v130
	v_mul_f32_e32 v163, 0xbfb8aa3b, v131
	v_mul_f32_e32 v164, 0xbfb8aa3b, v132
	v_mul_f32_e32 v165, 0xbfb8aa3b, v133
	v_mul_f32_e32 v166, 0xbfb8aa3b, v134
	v_mul_f32_e32 v167, 0xbfb8aa3b, v135
	v_mul_f32_e32 v168, 0xbfb8aa3b, v136
	v_mul_f32_e32 v169, 0xbfb8aa3b, v137
	v_mul_f32_e32 v170, 0xbfb8aa3b, v138
	v_mul_f32_e32 v171, 0xbfb8aa3b, v139
	v_mul_f32_e32 v172, 0xbfb8aa3b, v140
	v_mul_f32_e32 v173, 0xbfb8aa3b, v141
	v_mul_f32_e32 v174, 0xbfb8aa3b, v142
	v_mul_f32_e32 v175, 0xbfb8aa3b, v143
	v_mul_f32_e32 v176, 0xbfb8aa3b, v144
	v_mul_f32_e32 v177, 0xbfb8aa3b, v145
	v_mul_f32_e32 v178, 0xbfb8aa3b, v146
	v_mul_f32_e32 v179, 0xbfb8aa3b, v147
	v_mul_f32_e32 v180, 0xbfb8aa3b, v148
	v_mul_f32_e32 v181, 0xbfb8aa3b, v149
	v_mul_f32_e32 v182, 0xbfb8aa3b, v150
	v_mul_f32_e32 v183, 0xbfb8aa3b, v151
	v_mul_f32_e32 v184, 0xbfb8aa3b, v152
	v_mul_f32_e32 v185, 0xbfb8aa3b, v153
	v_mul_f32_e32 v186, 0xbfb8aa3b, v154
	v_mul_f32_e32 v187, 0xbfb8aa3b, v155
	v_mul_f32_e32 v188, 0xbfb8aa3b, v156
	v_mul_f32_e32 v189, 0xbfb8aa3b, v157
	v_mul_f32_e32 v190, 0xbfb8aa3b, v158
	v_mul_f32_e32 v191, 0xbfb8aa3b, v159
	v_exp_f32_e32 v160, v160
	v_exp_f32_e32 v161, v161
	v_exp_f32_e32 v162, v162
	v_exp_f32_e32 v163, v163
	v_exp_f32_e32 v164, v164
	v_exp_f32_e32 v165, v165
	v_exp_f32_e32 v166, v166
	v_exp_f32_e32 v167, v167
	v_exp_f32_e32 v168, v168
	v_exp_f32_e32 v169, v169
	v_exp_f32_e32 v170, v170
	v_exp_f32_e32 v171, v171
	v_exp_f32_e32 v172, v172
	v_exp_f32_e32 v173, v173
	v_exp_f32_e32 v174, v174
	v_exp_f32_e32 v175, v175
	v_exp_f32_e32 v176, v176
	v_exp_f32_e32 v177, v177
	v_exp_f32_e32 v178, v178
	v_exp_f32_e32 v179, v179
	v_exp_f32_e32 v180, v180
	v_exp_f32_e32 v181, v181
	v_exp_f32_e32 v182, v182
	v_exp_f32_e32 v183, v183
	v_exp_f32_e32 v184, v184
	v_exp_f32_e32 v185, v185
	v_exp_f32_e32 v186, v186
	v_exp_f32_e32 v187, v187
	v_exp_f32_e32 v188, v188
	v_exp_f32_e32 v189, v189
	v_exp_f32_e32 v190, v190
	v_exp_f32_e32 v191, v191
	v_add_f32_e32 v160, 1.0, v160
	v_add_f32_e32 v161, 1.0, v161
	v_add_f32_e32 v162, 1.0, v162
	v_add_f32_e32 v163, 1.0, v163
	v_add_f32_e32 v164, 1.0, v164
	v_add_f32_e32 v165, 1.0, v165
	v_add_f32_e32 v166, 1.0, v166
	v_add_f32_e32 v167, 1.0, v167
	v_add_f32_e32 v168, 1.0, v168
	v_add_f32_e32 v169, 1.0, v169
	v_add_f32_e32 v170, 1.0, v170
	v_add_f32_e32 v171, 1.0, v171
	v_add_f32_e32 v172, 1.0, v172
	v_add_f32_e32 v173, 1.0, v173
	v_add_f32_e32 v174, 1.0, v174
	v_add_f32_e32 v175, 1.0, v175
	v_add_f32_e32 v176, 1.0, v176
	v_add_f32_e32 v177, 1.0, v177
	v_add_f32_e32 v178, 1.0, v178
	v_add_f32_e32 v179, 1.0, v179
	v_add_f32_e32 v180, 1.0, v180
	v_add_f32_e32 v181, 1.0, v181
	v_add_f32_e32 v182, 1.0, v182
	v_add_f32_e32 v183, 1.0, v183
	v_add_f32_e32 v184, 1.0, v184
	v_add_f32_e32 v185, 1.0, v185
	v_add_f32_e32 v186, 1.0, v186
	v_add_f32_e32 v187, 1.0, v187
	v_add_f32_e32 v188, 1.0, v188
	v_add_f32_e32 v189, 1.0, v189
	v_add_f32_e32 v190, 1.0, v190
	v_add_f32_e32 v191, 1.0, v191
	v_rcp_f32_e32 v160, v160
	v_rcp_f32_e32 v161, v161
	v_rcp_f32_e32 v162, v162
	v_rcp_f32_e32 v163, v163
	v_rcp_f32_e32 v164, v164
	v_rcp_f32_e32 v165, v165
	v_rcp_f32_e32 v166, v166
	v_rcp_f32_e32 v167, v167
	v_rcp_f32_e32 v168, v168
	v_rcp_f32_e32 v169, v169
	v_rcp_f32_e32 v170, v170
	v_rcp_f32_e32 v171, v171
	v_rcp_f32_e32 v172, v172
	v_rcp_f32_e32 v173, v173
	v_rcp_f32_e32 v174, v174
	v_rcp_f32_e32 v175, v175
	v_rcp_f32_e32 v176, v176
	v_rcp_f32_e32 v177, v177
	v_rcp_f32_e32 v178, v178
	v_rcp_f32_e32 v179, v179
	v_rcp_f32_e32 v180, v180
	v_rcp_f32_e32 v181, v181
	v_rcp_f32_e32 v182, v182
	v_rcp_f32_e32 v183, v183
	v_rcp_f32_e32 v184, v184
	v_rcp_f32_e32 v185, v185
	v_rcp_f32_e32 v186, v186
	v_rcp_f32_e32 v187, v187
	v_rcp_f32_e32 v188, v188
	v_rcp_f32_e32 v189, v189
	v_rcp_f32_e32 v190, v190
	v_rcp_f32_e32 v191, v191
	v_mul_f32_e32 v128, v160, v128
	v_mul_f32_e32 v129, v161, v129
	v_mul_f32_e32 v130, v162, v130
	v_mul_f32_e32 v131, v163, v131
	v_mul_f32_e32 v132, v164, v132
	v_mul_f32_e32 v133, v165, v133
	v_mul_f32_e32 v134, v166, v134
	v_mul_f32_e32 v135, v167, v135
	v_mul_f32_e32 v136, v168, v136
	v_mul_f32_e32 v137, v169, v137
	v_mul_f32_e32 v138, v170, v138
	v_mul_f32_e32 v139, v171, v139
	v_mul_f32_e32 v140, v172, v140
	v_mul_f32_e32 v141, v173, v141
	v_mul_f32_e32 v142, v174, v142
	v_mul_f32_e32 v143, v175, v143
	v_mul_f32_e32 v144, v176, v144
	v_mul_f32_e32 v145, v177, v145
	v_mul_f32_e32 v146, v178, v146
	v_mul_f32_e32 v147, v179, v147
	v_mul_f32_e32 v148, v180, v148
	v_mul_f32_e32 v149, v181, v149
	v_mul_f32_e32 v150, v182, v150
	v_mul_f32_e32 v151, v183, v151
	v_mul_f32_e32 v152, v184, v152
	v_mul_f32_e32 v153, v185, v153
	v_mul_f32_e32 v154, v186, v154
	v_mul_f32_e32 v155, v187, v155
	v_mul_f32_e32 v156, v188, v156
	v_mul_f32_e32 v157, v189, v157
	v_mul_f32_e32 v158, v190, v158
	v_mul_f32_e32 v159, v191, v159
	v_mul_f32_e32 v128, v128, v96
	v_mul_f32_e32 v129, v129, v97
	v_mul_f32_e32 v130, v130, v98
	v_mul_f32_e32 v131, v131, v99
	v_mul_f32_e32 v132, v132, v100
	v_mul_f32_e32 v133, v133, v101
	v_mul_f32_e32 v134, v134, v102
	v_mul_f32_e32 v135, v135, v103
	v_mul_f32_e32 v136, v136, v104
	v_mul_f32_e32 v137, v137, v105
	v_mul_f32_e32 v138, v138, v106
	v_mul_f32_e32 v139, v139, v107
	v_mul_f32_e32 v140, v140, v108
	v_mul_f32_e32 v141, v141, v109
	v_mul_f32_e32 v142, v142, v110
	v_mul_f32_e32 v143, v143, v111
	v_mul_f32_e32 v144, v144, v112
	v_mul_f32_e32 v145, v145, v113
	v_mul_f32_e32 v146, v146, v114
	v_mul_f32_e32 v147, v147, v115
	v_mul_f32_e32 v148, v148, v116
	v_mul_f32_e32 v149, v149, v117
	v_mul_f32_e32 v150, v150, v118
	v_mul_f32_e32 v151, v151, v119
	v_mul_f32_e32 v152, v152, v120
	v_mul_f32_e32 v153, v153, v121
	v_mul_f32_e32 v154, v154, v122
	v_mul_f32_e32 v155, v155, v123
	v_mul_f32_e32 v156, v156, v124
	v_mul_f32_e32 v157, v157, v125
	v_mul_f32_e32 v158, v158, v126
	v_mul_f32_e32 v159, v159, v127
	v_mul_f32_e32 v128, v128, v200
	v_mul_f32_e32 v129, v129, v200
	v_mul_f32_e32 v130, v130, v200
	v_mul_f32_e32 v131, v131, v200
	v_mul_f32_e32 v132, v132, v200
	v_mul_f32_e32 v133, v133, v200
	v_mul_f32_e32 v134, v134, v200
	v_mul_f32_e32 v135, v135, v200
	v_mul_f32_e32 v136, v136, v201
	v_mul_f32_e32 v137, v137, v201
	v_mul_f32_e32 v138, v138, v201
	v_mul_f32_e32 v139, v139, v201
	v_mul_f32_e32 v140, v140, v201
	v_mul_f32_e32 v141, v141, v201
	v_mul_f32_e32 v142, v142, v201
	v_mul_f32_e32 v143, v143, v201
	v_mul_f32_e32 v144, v144, v202
	v_mul_f32_e32 v145, v145, v202
	v_mul_f32_e32 v146, v146, v202
	v_mul_f32_e32 v147, v147, v202
	v_mul_f32_e32 v148, v148, v202
	v_mul_f32_e32 v149, v149, v202
	v_mul_f32_e32 v150, v150, v202
	v_mul_f32_e32 v151, v151, v202
	v_mul_f32_e32 v152, v152, v203
	v_mul_f32_e32 v153, v153, v203
	v_mul_f32_e32 v154, v154, v203
	v_mul_f32_e32 v155, v155, v203
	v_mul_f32_e32 v156, v156, v203
	v_mul_f32_e32 v157, v157, v203
	v_mul_f32_e32 v158, v158, v203
	v_mul_f32_e32 v159, v159, v203
	v_cvt_pk_bf16_f32 v204, v128, v129
	v_cvt_pk_bf16_f32 v205, v130, v131
	v_cvt_pk_bf16_f32 v206, v132, v133
	v_cvt_pk_bf16_f32 v207, v134, v135
	v_cvt_pk_bf16_f32 v208, v136, v137
	v_cvt_pk_bf16_f32 v209, v138, v139
	v_cvt_pk_bf16_f32 v210, v140, v141
	v_cvt_pk_bf16_f32 v211, v142, v143
	v_cvt_pk_bf16_f32 v212, v144, v145
	v_cvt_pk_bf16_f32 v213, v146, v147
	v_cvt_pk_bf16_f32 v214, v148, v149
	v_cvt_pk_bf16_f32 v215, v150, v151
	v_cvt_pk_bf16_f32 v216, v152, v153
	v_cvt_pk_bf16_f32 v217, v154, v155
	v_cvt_pk_bf16_f32 v218, v156, v157
	v_cvt_pk_bf16_f32 v219, v158, v159
	global_store_dwordx4 v222, v[204:207], s[16:17]
	global_store_dwordx4 v222, v[208:211], s[16:17] offset:1024
	global_store_dwordx4 v222, v[212:215], s[16:17] offset:2048
	global_store_dwordx4 v222, v[216:219], s[16:17] offset:3072
	s_cmpk_lt_i32 s21, 0x4000
	s_cbranch_scc0 .Lgate1_done
	s_mov_b32 s20, s21
	s_mov_b64 s[16:17], s[14:15]
	s_add_i32 s21, s20, s82
	s_cmpk_lt_i32 s21, 0x4000
	s_cbranch_scc0 .Lgate1_nopfB
	s_lshl_b32 s0, s21, 1
	s_and_b32 s0, s0, 0xffffe000
	s_and_b32 s1, s21, 0xfff
	s_or_b32 s0, s0, s1
	s_bitset1_b32 s0, 12
	s_mulk_i32 s0, 0x3000
	s_add_u32 s14, s62, s0
	s_addc_u32 s15, s63, 0
	s_cmpk_lt_i32 s21, 0x2000
	s_cselect_b32 s18, s60, s27
	s_cselect_b32 s19, s61, s44
	s_lshl_b32 s0, s21, 12
	s_and_b32 s0, s0, 0x1fff000
	s_add_u32 s18, s18, s0
	s_addc_u32 s19, s19, 0
	global_load_dwordx4 v[0:3], v221, s[14:15] nt
	global_load_dwordx4 v[16:19], v222, s[14:15] nt
	global_load_dwordx4 v[32:35], v220, s[18:19] nt
	global_load_dwordx4 v[4:7], v221, s[14:15] offset:1024 nt
	global_load_dwordx4 v[20:23], v222, s[14:15] offset:1024 nt
	global_load_dwordx4 v[36:39], v220, s[18:19] offset:1024 nt
	global_load_dwordx4 v[8:11], v221, s[14:15] offset:2048 nt
	global_load_dwordx4 v[24:27], v222, s[14:15] offset:2048 nt
	global_load_dwordx4 v[40:43], v220, s[18:19] offset:2048 nt
	global_load_dwordx4 v[12:15], v221, s[14:15] offset:3072 nt
	global_load_dwordx4 v[28:31], v222, s[14:15] offset:3072 nt
	global_load_dwordx4 v[44:47], v220, s[18:19] offset:3072 nt
	s_waitcnt vmcnt(16)
	s_branch .Lgate1_goB

.Lgate1_goB:
	v_lshlrev_b32_e32 v96, 16, v48
	v_and_b32_e32 v97, 0xffff0000, v48
	v_lshlrev_b32_e32 v160, 16, v80
	v_and_b32_e32 v161, 0xffff0000, v80
	v_lshlrev_b32_e32 v98, 16, v49
	v_and_b32_e32 v99, 0xffff0000, v49
	v_lshlrev_b32_e32 v162, 16, v81
	v_and_b32_e32 v163, 0xffff0000, v81
	v_lshlrev_b32_e32 v100, 16, v50
	v_and_b32_e32 v101, 0xffff0000, v50
	v_lshlrev_b32_e32 v164, 16, v82
	v_and_b32_e32 v165, 0xffff0000, v82
	v_lshlrev_b32_e32 v102, 16, v51
	v_and_b32_e32 v103, 0xffff0000, v51
	v_lshlrev_b32_e32 v166, 16, v83
	v_and_b32_e32 v167, 0xffff0000, v83
	v_add_f32_e32 v96, v96, v160
	v_add_f32_e32 v97, v97, v161
	v_add_f32_e32 v98, v98, v162
	v_add_f32_e32 v99, v99, v163
	v_add_f32_e32 v100, v100, v164
	v_add_f32_e32 v101, v101, v165
	v_add_f32_e32 v102, v102, v166
	v_add_f32_e32 v103, v103, v167
	v_cvt_pk_bf16_f32 v160, v96, v97
	v_cvt_pk_bf16_f32 v161, v98, v99
	v_cvt_pk_bf16_f32 v162, v100, v101
	v_cvt_pk_bf16_f32 v163, v102, v103
	v_lshlrev_b32_e32 v96, 16, v160
	v_and_b32_e32 v97, 0xffff0000, v160
	v_lshlrev_b32_e32 v98, 16, v161
	v_and_b32_e32 v99, 0xffff0000, v161
	v_lshlrev_b32_e32 v100, 16, v162
	v_and_b32_e32 v101, 0xffff0000, v162
	v_lshlrev_b32_e32 v102, 16, v163
	v_and_b32_e32 v103, 0xffff0000, v163
	v_mul_f32_e32 v192, v96, v96
	v_fmac_f32_e32 v192, v97, v97
	v_fmac_f32_e32 v192, v98, v98
	v_fmac_f32_e32 v192, v99, v99
	v_fmac_f32_e32 v192, v100, v100
	v_fmac_f32_e32 v192, v101, v101
	v_fmac_f32_e32 v192, v102, v102
	v_fmac_f32_e32 v192, v103, v103
	v_lshlrev_b32_e32 v104, 16, v52
	v_and_b32_e32 v105, 0xffff0000, v52
	v_lshlrev_b32_e32 v168, 16, v84
	v_and_b32_e32 v169, 0xffff0000, v84
	v_lshlrev_b32_e32 v106, 16, v53
	v_and_b32_e32 v107, 0xffff0000, v53
	v_lshlrev_b32_e32 v170, 16, v85
	v_and_b32_e32 v171, 0xffff0000, v85
	v_lshlrev_b32_e32 v108, 16, v54
	v_and_b32_e32 v109, 0xffff0000, v54
	v_lshlrev_b32_e32 v172, 16, v86
	v_and_b32_e32 v173, 0xffff0000, v86
	v_lshlrev_b32_e32 v110, 16, v55
	v_and_b32_e32 v111, 0xffff0000, v55
	v_lshlrev_b32_e32 v174, 16, v87
	v_and_b32_e32 v175, 0xffff0000, v87
	v_add_f32_e32 v104, v104, v168
	v_add_f32_e32 v105, v105, v169
	v_add_f32_e32 v106, v106, v170
	v_add_f32_e32 v107, v107, v171
	v_add_f32_e32 v108, v108, v172
	v_add_f32_e32 v109, v109, v173
	v_add_f32_e32 v110, v110, v174
	v_add_f32_e32 v111, v111, v175
	v_cvt_pk_bf16_f32 v168, v104, v105
	v_cvt_pk_bf16_f32 v169, v106, v107
	v_cvt_pk_bf16_f32 v170, v108, v109
	v_cvt_pk_bf16_f32 v171, v110, v111
	v_lshlrev_b32_e32 v104, 16, v168
	v_and_b32_e32 v105, 0xffff0000, v168
	v_lshlrev_b32_e32 v106, 16, v169
	v_and_b32_e32 v107, 0xffff0000, v169
	v_lshlrev_b32_e32 v108, 16, v170
	v_and_b32_e32 v109, 0xffff0000, v170
	v_lshlrev_b32_e32 v110, 16, v171
	v_and_b32_e32 v111, 0xffff0000, v171
	v_mul_f32_e32 v193, v104, v104
	v_fmac_f32_e32 v193, v105, v105
	v_fmac_f32_e32 v193, v106, v106
	v_fmac_f32_e32 v193, v107, v107
	v_fmac_f32_e32 v193, v108, v108
	v_fmac_f32_e32 v193, v109, v109
	v_fmac_f32_e32 v193, v110, v110
	v_fmac_f32_e32 v193, v111, v111
	v_lshlrev_b32_e32 v112, 16, v56
	v_and_b32_e32 v113, 0xffff0000, v56
	v_lshlrev_b32_e32 v176, 16, v88
	v_and_b32_e32 v177, 0xffff0000, v88
	v_lshlrev_b32_e32 v114, 16, v57
	v_and_b32_e32 v115, 0xffff0000, v57
	v_lshlrev_b32_e32 v178, 16, v89
	v_and_b32_e32 v179, 0xffff0000, v89
	v_lshlrev_b32_e32 v116, 16, v58
	v_and_b32_e32 v117, 0xffff0000, v58
	v_lshlrev_b32_e32 v180, 16, v90
	v_and_b32_e32 v181, 0xffff0000, v90
	v_lshlrev_b32_e32 v118, 16, v59
	v_and_b32_e32 v119, 0xffff0000, v59
	v_lshlrev_b32_e32 v182, 16, v91
	v_and_b32_e32 v183, 0xffff0000, v91
	v_add_f32_e32 v112, v112, v176
	v_add_f32_e32 v113, v113, v177
	v_add_f32_e32 v114, v114, v178
	v_add_f32_e32 v115, v115, v179
	v_add_f32_e32 v116, v116, v180
	v_add_f32_e32 v117, v117, v181
	v_add_f32_e32 v118, v118, v182
	v_add_f32_e32 v119, v119, v183
	v_cvt_pk_bf16_f32 v176, v112, v113
	v_cvt_pk_bf16_f32 v177, v114, v115
	v_cvt_pk_bf16_f32 v178, v116, v117
	v_cvt_pk_bf16_f32 v179, v118, v119
	v_lshlrev_b32_e32 v112, 16, v176
	v_and_b32_e32 v113, 0xffff0000, v176
	v_lshlrev_b32_e32 v114, 16, v177
	v_and_b32_e32 v115, 0xffff0000, v177
	v_lshlrev_b32_e32 v116, 16, v178
	v_and_b32_e32 v117, 0xffff0000, v178
	v_lshlrev_b32_e32 v118, 16, v179
	v_and_b32_e32 v119, 0xffff0000, v179
	v_mul_f32_e32 v194, v112, v112
	v_fmac_f32_e32 v194, v113, v113
	v_fmac_f32_e32 v194, v114, v114
	v_fmac_f32_e32 v194, v115, v115
	v_fmac_f32_e32 v194, v116, v116
	v_fmac_f32_e32 v194, v117, v117
	v_fmac_f32_e32 v194, v118, v118
	v_fmac_f32_e32 v194, v119, v119
	v_lshlrev_b32_e32 v120, 16, v60
	v_and_b32_e32 v121, 0xffff0000, v60
	v_lshlrev_b32_e32 v184, 16, v92
	v_and_b32_e32 v185, 0xffff0000, v92
	v_lshlrev_b32_e32 v122, 16, v61
	v_and_b32_e32 v123, 0xffff0000, v61
	v_lshlrev_b32_e32 v186, 16, v93
	v_and_b32_e32 v187, 0xffff0000, v93
	v_lshlrev_b32_e32 v124, 16, v62
	v_and_b32_e32 v125, 0xffff0000, v62
	v_lshlrev_b32_e32 v188, 16, v94
	v_and_b32_e32 v189, 0xffff0000, v94
	v_lshlrev_b32_e32 v126, 16, v63
	v_and_b32_e32 v127, 0xffff0000, v63
	v_lshlrev_b32_e32 v190, 16, v95
	v_and_b32_e32 v191, 0xffff0000, v95
	v_add_f32_e32 v120, v120, v184
	v_add_f32_e32 v121, v121, v185
	v_add_f32_e32 v122, v122, v186
	v_add_f32_e32 v123, v123, v187
	v_add_f32_e32 v124, v124, v188
	v_add_f32_e32 v125, v125, v189
	v_add_f32_e32 v126, v126, v190
	v_add_f32_e32 v127, v127, v191
	v_cvt_pk_bf16_f32 v184, v120, v121
	v_cvt_pk_bf16_f32 v185, v122, v123
	v_cvt_pk_bf16_f32 v186, v124, v125
	v_cvt_pk_bf16_f32 v187, v126, v127
	v_lshlrev_b32_e32 v120, 16, v184
	v_and_b32_e32 v121, 0xffff0000, v184
	v_lshlrev_b32_e32 v122, 16, v185
	v_and_b32_e32 v123, 0xffff0000, v185
	v_lshlrev_b32_e32 v124, 16, v186
	v_and_b32_e32 v125, 0xffff0000, v186
	v_lshlrev_b32_e32 v126, 16, v187
	v_and_b32_e32 v127, 0xffff0000, v187
	v_mul_f32_e32 v195, v120, v120
	v_fmac_f32_e32 v195, v121, v121
	v_fmac_f32_e32 v195, v122, v122
	v_fmac_f32_e32 v195, v123, v123
	v_fmac_f32_e32 v195, v124, v124
	v_fmac_f32_e32 v195, v125, v125
	v_fmac_f32_e32 v195, v126, v126
	v_fmac_f32_e32 v195, v127, v127
	s_nop 1
	v_add_f32_dpp v196, v192, v192 quad_perm:[1,0,3,2] row_mask:0xf bank_mask:0xf
	v_add_f32_dpp v197, v193, v193 quad_perm:[1,0,3,2] row_mask:0xf bank_mask:0xf
	v_add_f32_dpp v198, v194, v194 quad_perm:[1,0,3,2] row_mask:0xf bank_mask:0xf
	v_add_f32_dpp v199, v195, v195 quad_perm:[1,0,3,2] row_mask:0xf bank_mask:0xf
	v_add_f32_dpp v192, v196, v196 quad_perm:[2,3,0,1] row_mask:0xf bank_mask:0xf
	v_add_f32_dpp v193, v197, v197 quad_perm:[2,3,0,1] row_mask:0xf bank_mask:0xf
	v_add_f32_dpp v194, v198, v198 quad_perm:[2,3,0,1] row_mask:0xf bank_mask:0xf
	v_add_f32_dpp v195, v199, v199 quad_perm:[2,3,0,1] row_mask:0xf bank_mask:0xf
	v_add_f32_dpp v196, v192, v192 row_half_mirror row_mask:0xf bank_mask:0xf
	v_add_f32_dpp v197, v193, v193 row_half_mirror row_mask:0xf bank_mask:0xf
	v_add_f32_dpp v198, v194, v194 row_half_mirror row_mask:0xf bank_mask:0xf
	v_add_f32_dpp v199, v195, v195 row_half_mirror row_mask:0xf bank_mask:0xf
	v_add_f32_dpp v192, v196, v196 row_mirror row_mask:0xf bank_mask:0xf
	v_add_f32_dpp v193, v197, v197 row_mirror row_mask:0xf bank_mask:0xf
	v_add_f32_dpp v194, v198, v198 row_mirror row_mask:0xf bank_mask:0xf
	v_add_f32_dpp v195, v199, v199 row_mirror row_mask:0xf bank_mask:0xf
	s_nop 0
	v_readlane_b32 s0, v192, 0
	v_readlane_b32 s1, v192, 16
	v_readlane_b32 s6, v192, 32
	v_readlane_b32 s7, v192, 48
	s_nop 1
	v_mov_b32_e32 v196, s0
	v_add_f32_e32 v196, s1, v196
	v_add_f32_e32 v196, s6, v196
	v_add_f32_e32 v196, s7, v196
	v_fmamk_f32 v196, v196, 0x3b000000, v223
	v_readlane_b32 s0, v193, 0
	v_readlane_b32 s1, v193, 16
	v_readlane_b32 s6, v193, 32
	v_readlane_b32 s7, v193, 48
	s_nop 1
	v_mov_b32_e32 v197, s0
	v_add_f32_e32 v197, s1, v197
	v_add_f32_e32 v197, s6, v197
	v_add_f32_e32 v197, s7, v197
	v_fmamk_f32 v197, v197, 0x3b000000, v223
	v_readlane_b32 s0, v194, 0
	v_readlane_b32 s1, v194, 16
	v_readlane_b32 s6, v194, 32
	v_readlane_b32 s7, v194, 48
	s_nop 1
	v_mov_b32_e32 v198, s0
	v_add_f32_e32 v198, s1, v198
	v_add_f32_e32 v198, s6, v198
	v_add_f32_e32 v198, s7, v198
	v_fmamk_f32 v198, v198, 0x3b000000, v223
	v_readlane_b32 s0, v195, 0
	v_readlane_b32 s1, v195, 16
	v_readlane_b32 s6, v195, 32
	v_readlane_b32 s7, v195, 48
	s_nop 1
	v_mov_b32_e32 v199, s0
	v_add_f32_e32 v199, s1, v199
	v_add_f32_e32 v199, s6, v199
	v_add_f32_e32 v199, s7, v199
	v_fmamk_f32 v199, v199, 0x3b000000, v223
	v_rsq_f32_e32 v200, v196
	v_rsq_f32_e32 v201, v197
	v_rsq_f32_e32 v202, v198
	v_rsq_f32_e32 v203, v199
	v_lshlrev_b32_e32 v128, 16, v64
	v_and_b32_e32 v129, 0xffff0000, v64
	v_lshlrev_b32_e32 v130, 16, v65
	v_and_b32_e32 v131, 0xffff0000, v65
	v_lshlrev_b32_e32 v132, 16, v66
	v_and_b32_e32 v133, 0xffff0000, v66
	v_lshlrev_b32_e32 v134, 16, v67
	v_and_b32_e32 v135, 0xffff0000, v67
	v_lshlrev_b32_e32 v136, 16, v68
	v_and_b32_e32 v137, 0xffff0000, v68
	v_lshlrev_b32_e32 v138, 16, v69
	v_and_b32_e32 v139, 0xffff0000, v69
	v_lshlrev_b32_e32 v140, 16, v70
	v_and_b32_e32 v141, 0xffff0000, v70
	v_lshlrev_b32_e32 v142, 16, v71
	v_and_b32_e32 v143, 0xffff0000, v71
	v_lshlrev_b32_e32 v144, 16, v72
	v_and_b32_e32 v145, 0xffff0000, v72
	v_lshlrev_b32_e32 v146, 16, v73
	v_and_b32_e32 v147, 0xffff0000, v73
	v_lshlrev_b32_e32 v148, 16, v74
	v_and_b32_e32 v149, 0xffff0000, v74
	v_lshlrev_b32_e32 v150, 16, v75
	v_and_b32_e32 v151, 0xffff0000, v75
	v_lshlrev_b32_e32 v152, 16, v76
	v_and_b32_e32 v153, 0xffff0000, v76
	v_lshlrev_b32_e32 v154, 16, v77
	v_and_b32_e32 v155, 0xffff0000, v77
	v_lshlrev_b32_e32 v156, 16, v78
	v_and_b32_e32 v157, 0xffff0000, v78
	v_lshlrev_b32_e32 v158, 16, v79
	v_and_b32_e32 v159, 0xffff0000, v79
	v_mul_f32_e32 v160, 0xbfb8aa3b, v128
	v_mul_f32_e32 v161, 0xbfb8aa3b, v129
	v_mul_f32_e32 v162, 0xbfb8aa3b, v130
	v_mul_f32_e32 v163, 0xbfb8aa3b, v131
	v_mul_f32_e32 v164, 0xbfb8aa3b, v132
	v_mul_f32_e32 v165, 0xbfb8aa3b, v133
	v_mul_f32_e32 v166, 0xbfb8aa3b, v134
	v_mul_f32_e32 v167, 0xbfb8aa3b, v135
	v_mul_f32_e32 v168, 0xbfb8aa3b, v136
	v_mul_f32_e32 v169, 0xbfb8aa3b, v137
	v_mul_f32_e32 v170, 0xbfb8aa3b, v138
	v_mul_f32_e32 v171, 0xbfb8aa3b, v139
	v_mul_f32_e32 v172, 0xbfb8aa3b, v140
	v_mul_f32_e32 v173, 0xbfb8aa3b, v141
	v_mul_f32_e32 v174, 0xbfb8aa3b, v142
	v_mul_f32_e32 v175, 0xbfb8aa3b, v143
	v_mul_f32_e32 v176, 0xbfb8aa3b, v144
	v_mul_f32_e32 v177, 0xbfb8aa3b, v145
	v_mul_f32_e32 v178, 0xbfb8aa3b, v146
	v_mul_f32_e32 v179, 0xbfb8aa3b, v147
	v_mul_f32_e32 v180, 0xbfb8aa3b, v148
	v_mul_f32_e32 v181, 0xbfb8aa3b, v149
	v_mul_f32_e32 v182, 0xbfb8aa3b, v150
	v_mul_f32_e32 v183, 0xbfb8aa3b, v151
	v_mul_f32_e32 v184, 0xbfb8aa3b, v152
	v_mul_f32_e32 v185, 0xbfb8aa3b, v153
	v_mul_f32_e32 v186, 0xbfb8aa3b, v154
	v_mul_f32_e32 v187, 0xbfb8aa3b, v155
	v_mul_f32_e32 v188, 0xbfb8aa3b, v156
	v_mul_f32_e32 v189, 0xbfb8aa3b, v157
	v_mul_f32_e32 v190, 0xbfb8aa3b, v158
	v_mul_f32_e32 v191, 0xbfb8aa3b, v159
	v_exp_f32_e32 v160, v160
	v_exp_f32_e32 v161, v161
	v_exp_f32_e32 v162, v162
	v_exp_f32_e32 v163, v163
	v_exp_f32_e32 v164, v164
	v_exp_f32_e32 v165, v165
	v_exp_f32_e32 v166, v166
	v_exp_f32_e32 v167, v167
	v_exp_f32_e32 v168, v168
	v_exp_f32_e32 v169, v169
	v_exp_f32_e32 v170, v170
	v_exp_f32_e32 v171, v171
	v_exp_f32_e32 v172, v172
	v_exp_f32_e32 v173, v173
	v_exp_f32_e32 v174, v174
	v_exp_f32_e32 v175, v175
	v_exp_f32_e32 v176, v176
	v_exp_f32_e32 v177, v177
	v_exp_f32_e32 v178, v178
	v_exp_f32_e32 v179, v179
	v_exp_f32_e32 v180, v180
	v_exp_f32_e32 v181, v181
	v_exp_f32_e32 v182, v182
	v_exp_f32_e32 v183, v183
	v_exp_f32_e32 v184, v184
	v_exp_f32_e32 v185, v185
	v_exp_f32_e32 v186, v186
	v_exp_f32_e32 v187, v187
	v_exp_f32_e32 v188, v188
	v_exp_f32_e32 v189, v189
	v_exp_f32_e32 v190, v190
	v_exp_f32_e32 v191, v191
	v_add_f32_e32 v160, 1.0, v160
	v_add_f32_e32 v161, 1.0, v161
	v_add_f32_e32 v162, 1.0, v162
	v_add_f32_e32 v163, 1.0, v163
	v_add_f32_e32 v164, 1.0, v164
	v_add_f32_e32 v165, 1.0, v165
	v_add_f32_e32 v166, 1.0, v166
	v_add_f32_e32 v167, 1.0, v167
	v_add_f32_e32 v168, 1.0, v168
	v_add_f32_e32 v169, 1.0, v169
	v_add_f32_e32 v170, 1.0, v170
	v_add_f32_e32 v171, 1.0, v171
	v_add_f32_e32 v172, 1.0, v172
	v_add_f32_e32 v173, 1.0, v173
	v_add_f32_e32 v174, 1.0, v174
	v_add_f32_e32 v175, 1.0, v175
	v_add_f32_e32 v176, 1.0, v176
	v_add_f32_e32 v177, 1.0, v177
	v_add_f32_e32 v178, 1.0, v178
	v_add_f32_e32 v179, 1.0, v179
	v_add_f32_e32 v180, 1.0, v180
	v_add_f32_e32 v181, 1.0, v181
	v_add_f32_e32 v182, 1.0, v182
	v_add_f32_e32 v183, 1.0, v183
	v_add_f32_e32 v184, 1.0, v184
	v_add_f32_e32 v185, 1.0, v185
	v_add_f32_e32 v186, 1.0, v186
	v_add_f32_e32 v187, 1.0, v187
	v_add_f32_e32 v188, 1.0, v188
	v_add_f32_e32 v189, 1.0, v189
	v_add_f32_e32 v190, 1.0, v190
	v_add_f32_e32 v191, 1.0, v191
	v_rcp_f32_e32 v160, v160
	v_rcp_f32_e32 v161, v161
	v_rcp_f32_e32 v162, v162
	v_rcp_f32_e32 v163, v163
	v_rcp_f32_e32 v164, v164
	v_rcp_f32_e32 v165, v165
	v_rcp_f32_e32 v166, v166
	v_rcp_f32_e32 v167, v167
	v_rcp_f32_e32 v168, v168
	v_rcp_f32_e32 v169, v169
	v_rcp_f32_e32 v170, v170
	v_rcp_f32_e32 v171, v171
	v_rcp_f32_e32 v172, v172
	v_rcp_f32_e32 v173, v173
	v_rcp_f32_e32 v174, v174
	v_rcp_f32_e32 v175, v175
	v_rcp_f32_e32 v176, v176
	v_rcp_f32_e32 v177, v177
	v_rcp_f32_e32 v178, v178
	v_rcp_f32_e32 v179, v179
	v_rcp_f32_e32 v180, v180
	v_rcp_f32_e32 v181, v181
	v_rcp_f32_e32 v182, v182
	v_rcp_f32_e32 v183, v183
	v_rcp_f32_e32 v184, v184
	v_rcp_f32_e32 v185, v185
	v_rcp_f32_e32 v186, v186
	v_rcp_f32_e32 v187, v187
	v_rcp_f32_e32 v188, v188
	v_rcp_f32_e32 v189, v189
	v_rcp_f32_e32 v190, v190
	v_rcp_f32_e32 v191, v191
	v_mul_f32_e32 v128, v160, v128
	v_mul_f32_e32 v129, v161, v129
	v_mul_f32_e32 v130, v162, v130
	v_mul_f32_e32 v131, v163, v131
	v_mul_f32_e32 v132, v164, v132
	v_mul_f32_e32 v133, v165, v133
	v_mul_f32_e32 v134, v166, v134
	v_mul_f32_e32 v135, v167, v135
	v_mul_f32_e32 v136, v168, v136
	v_mul_f32_e32 v137, v169, v137
	v_mul_f32_e32 v138, v170, v138
	v_mul_f32_e32 v139, v171, v139
	v_mul_f32_e32 v140, v172, v140
	v_mul_f32_e32 v141, v173, v141
	v_mul_f32_e32 v142, v174, v142
	v_mul_f32_e32 v143, v175, v143
	v_mul_f32_e32 v144, v176, v144
	v_mul_f32_e32 v145, v177, v145
	v_mul_f32_e32 v146, v178, v146
	v_mul_f32_e32 v147, v179, v147
	v_mul_f32_e32 v148, v180, v148
	v_mul_f32_e32 v149, v181, v149
	v_mul_f32_e32 v150, v182, v150
	v_mul_f32_e32 v151, v183, v151
	v_mul_f32_e32 v152, v184, v152
	v_mul_f32_e32 v153, v185, v153
	v_mul_f32_e32 v154, v186, v154
	v_mul_f32_e32 v155, v187, v155
	v_mul_f32_e32 v156, v188, v156
	v_mul_f32_e32 v157, v189, v157
	v_mul_f32_e32 v158, v190, v158
	v_mul_f32_e32 v159, v191, v159
	v_mul_f32_e32 v128, v128, v96
	v_mul_f32_e32 v129, v129, v97
	v_mul_f32_e32 v130, v130, v98
	v_mul_f32_e32 v131, v131, v99
	v_mul_f32_e32 v132, v132, v100
	v_mul_f32_e32 v133, v133, v101
	v_mul_f32_e32 v134, v134, v102
	v_mul_f32_e32 v135, v135, v103
	v_mul_f32_e32 v136, v136, v104
	v_mul_f32_e32 v137, v137, v105
	v_mul_f32_e32 v138, v138, v106
	v_mul_f32_e32 v139, v139, v107
	v_mul_f32_e32 v140, v140, v108
	v_mul_f32_e32 v141, v141, v109
	v_mul_f32_e32 v142, v142, v110
	v_mul_f32_e32 v143, v143, v111
	v_mul_f32_e32 v144, v144, v112
	v_mul_f32_e32 v145, v145, v113
	v_mul_f32_e32 v146, v146, v114
	v_mul_f32_e32 v147, v147, v115
	v_mul_f32_e32 v148, v148, v116
	v_mul_f32_e32 v149, v149, v117
	v_mul_f32_e32 v150, v150, v118
	v_mul_f32_e32 v151, v151, v119
	v_mul_f32_e32 v152, v152, v120
	v_mul_f32_e32 v153, v153, v121
	v_mul_f32_e32 v154, v154, v122
	v_mul_f32_e32 v155, v155, v123
	v_mul_f32_e32 v156, v156, v124
	v_mul_f32_e32 v157, v157, v125
	v_mul_f32_e32 v158, v158, v126
	v_mul_f32_e32 v159, v159, v127
	v_mul_f32_e32 v128, v128, v200
	v_mul_f32_e32 v129, v129, v200
	v_mul_f32_e32 v130, v130, v200
	v_mul_f32_e32 v131, v131, v200
	v_mul_f32_e32 v132, v132, v200
	v_mul_f32_e32 v133, v133, v200
	v_mul_f32_e32 v134, v134, v200
	v_mul_f32_e32 v135, v135, v200
	v_mul_f32_e32 v136, v136, v201
	v_mul_f32_e32 v137, v137, v201
	v_mul_f32_e32 v138, v138, v201
	v_mul_f32_e32 v139, v139, v201
	v_mul_f32_e32 v140, v140, v201
	v_mul_f32_e32 v141, v141, v201
	v_mul_f32_e32 v142, v142, v201
	v_mul_f32_e32 v143, v143, v201
	v_mul_f32_e32 v144, v144, v202
	v_mul_f32_e32 v145, v145, v202
	v_mul_f32_e32 v146, v146, v202
	v_mul_f32_e32 v147, v147, v202
	v_mul_f32_e32 v148, v148, v202
	v_mul_f32_e32 v149, v149, v202
	v_mul_f32_e32 v150, v150, v202
	v_mul_f32_e32 v151, v151, v202
	v_mul_f32_e32 v152, v152, v203
	v_mul_f32_e32 v153, v153, v203
	v_mul_f32_e32 v154, v154, v203
	v_mul_f32_e32 v155, v155, v203
	v_mul_f32_e32 v156, v156, v203
	v_mul_f32_e32 v157, v157, v203
	v_mul_f32_e32 v158, v158, v203
	v_mul_f32_e32 v159, v159, v203
	v_cvt_pk_bf16_f32 v204, v128, v129
	v_cvt_pk_bf16_f32 v205, v130, v131
	v_cvt_pk_bf16_f32 v206, v132, v133
	v_cvt_pk_bf16_f32 v207, v134, v135
	v_cvt_pk_bf16_f32 v208, v136, v137
	v_cvt_pk_bf16_f32 v209, v138, v139
	v_cvt_pk_bf16_f32 v210, v140, v141
	v_cvt_pk_bf16_f32 v211, v142, v143
	v_cvt_pk_bf16_f32 v212, v144, v145
	v_cvt_pk_bf16_f32 v213, v146, v147
	v_cvt_pk_bf16_f32 v214, v148, v149
	v_cvt_pk_bf16_f32 v215, v150, v151
	v_cvt_pk_bf16_f32 v216, v152, v153
	v_cvt_pk_bf16_f32 v217, v154, v155
	v_cvt_pk_bf16_f32 v218, v156, v157
	v_cvt_pk_bf16_f32 v219, v158, v159
	global_store_dwordx4 v222, v[204:207], s[16:17]
	global_store_dwordx4 v222, v[208:211], s[16:17] offset:1024
	global_store_dwordx4 v222, v[212:215], s[16:17] offset:2048
	global_store_dwordx4 v222, v[216:219], s[16:17] offset:3072
	s_cmpk_lt_i32 s21, 0x4000
	s_cbranch_scc0 .Lgate1_done
	s_mov_b32 s20, s21
	s_mov_b64 s[16:17], s[14:15]
	s_branch .Lgate1_topA
